# blockhead-all8-loops
# baseline (speedup 1.0000x reference)
; #define PG8_STAGEA(bufoff, goff, voff) PG8_STAGEX(rsA, bufoff, goff, voff)
; #define PG8_STAGEB(bufoff, goff, voff) PG8_STAGEX(rsB, bufoff, goff, voff)
; #define PG8_LDA(dst, b, h) do { _Pragma("unroll") for (int m = 0; m < 4; ++m) _Pragma("unroll") for (int k = 0; k < 2; ++k) dst[m][k] = *(const PG8_LAS bf16x8*)(lds + PG8_SA(b, h) + aoff + m * 2048 + k * 1024); } while (0)
; #define PG8_MMA(ai, bj, At, Bt) do { __builtin_amdgcn_s_setprio(1); _Pragma("unroll") for (int m = 0; m < 4; ++m) _Pragma("unroll") for (int n = 0; n < 2; ++n) _Pragma("unroll") for (int k = 0; k < 2; ++k) \
;         acc[ai][bj][m][n] = __builtin_amdgcn_mfma_f32_16x16x32_bf16(Bt[n][k], At[m][k], acc[ai][bj][m][n], 0, 0, 0); __builtin_amdgcn_s_setprio(0); } while (0)
; #define PG8_WAIT_V(n) asm volatile("s_waitcnt vmcnt(" #n ")" ::: "memory")
; #define PG8_WAIT_L(n) asm volatile("s_waitcnt lgkmcnt(" #n ")" ::: "memory")
; #define PG8_BAR __builtin_amdgcn_s_barrier()
; #define PG8_SCHED __builtin_amdgcn_sched_barrier(0)
; template <class Epi, class Sched, bool ALIGN_EPI = false, bool SP2 = false>
; __device__ __forceinline__ void gemm_phase(PG8_LAS unsigned char* lds, const Gemm g, const Sched& S, const Epi& E) {
;     ...
;         const size_t nA = has_next ? (size_t)nxt.pm * tstep : cA; const size_t nB = has_next ? (size_t)nxt.pn * tstep : cB;
;         for (int t = 0; t < nt; t += 2) {
;             const bool last = (t == nt - 2);
;             if constexpr (Epi::MIDK) { if (t == (nt >> 1)) E.midk(acc, wr, fr, lds); }
;             const size_t a1 = cA + (size_t)(t + 1) * kstep;
;             const size_t a2 = last ? nA : cA + (size_t)(t + 2) * kstep; const size_t b2 = last ? nB : cB + (size_t)(t + 2) * kstep;
;     ...
;             PG8_WAIT_V(8); PG8_WAIT_L(0); PG8_BAR; PG8_MMA(0, 0, At, B0); PG8_MMA(0, 1, At, B1); PG8_BAR; PG8_SCHED;
;             PG8_LDA(At, 0, 1); PG8_STAGEB(PG8_SB(0, 0), b2, voffB); PG8_STAGEB(PG8_SB(0, 1), b2 + hstep, voffB); PG8_STAGEA(PG8_SA(0, 0), a2, voffA);
;             PG8_WAIT_V(8); PG8_WAIT_L(0); PG8_BAR; PG8_MMA(1, 0, At, B0); PG8_MMA(1, 1, At, B1); PG8_BAR; PG8_SCHED;
.LBB0_676:
	s_ashr_i32 s23, s22, 31
	s_lshl_b64 s[34:35], s[22:23], 20
	s_and_b64 s[36:37], vcc, exec
	s_cselect_b32 s19, s34, s18
	s_ashr_i32 s21, s20, 31
	s_waitcnt vmcnt(8)
	s_lshl_b64 s[36:37], s[20:21], 20
	s_waitcnt lgkmcnt(0)
	s_and_b64 s[38:39], vcc, exec
	s_cselect_b32 s21, s36, s16
	s_add_u32 s23, s16, 0x200
	s_setprio 1
	s_barrier
	v_mfma_f32_16x16x32_bf16 v[126:129], v[146:149], v[186:189], v[126:129]
	v_mfma_f32_16x16x32_bf16 v[122:125], v[154:157], v[186:189], v[122:125]
	v_mfma_f32_16x16x32_bf16 v[114:117], v[146:149], v[178:181], v[114:117]
	v_mfma_f32_16x16x32_bf16 v[106:109], v[154:157], v[178:181], v[106:109]
	v_mfma_f32_16x16x32_bf16 v[98:101], v[146:149], v[170:173], v[98:101]
	v_mfma_f32_16x16x32_bf16 v[90:93], v[154:157], v[170:173], v[90:93]
	v_mfma_f32_16x16x32_bf16 v[82:85], v[146:149], v[162:165], v[82:85]
	v_mfma_f32_16x16x32_bf16 v[74:77], v[154:157], v[162:165], v[74:77]
	v_mfma_f32_16x16x32_bf16 v[126:129], v[150:153], v[190:193], v[126:129]
	v_mfma_f32_16x16x32_bf16 v[122:125], v[158:161], v[190:193], v[122:125]
	v_mfma_f32_16x16x32_bf16 v[114:117], v[150:153], v[182:185], v[114:117]
	v_mfma_f32_16x16x32_bf16 v[106:109], v[158:161], v[182:185], v[106:109]
	v_mfma_f32_16x16x32_bf16 v[98:101], v[150:153], v[174:177], v[98:101]
	v_mfma_f32_16x16x32_bf16 v[90:93], v[158:161], v[174:177], v[90:93]
	v_mfma_f32_16x16x32_bf16 v[82:85], v[150:153], v[166:169], v[82:85]
	v_mfma_f32_16x16x32_bf16 v[74:77], v[158:161], v[166:169], v[74:77]
	v_mfma_f32_16x16x32_bf16 v[118:121], v[130:133], v[186:189], v[118:121]
	v_mfma_f32_16x16x32_bf16 v[110:113], v[138:141], v[186:189], v[110:113]
	v_mfma_f32_16x16x32_bf16 v[102:105], v[130:133], v[178:181], v[102:105]
	v_mfma_f32_16x16x32_bf16 v[94:97], v[138:141], v[178:181], v[94:97]
	v_mfma_f32_16x16x32_bf16 v[86:89], v[130:133], v[170:173], v[86:89]
	v_mfma_f32_16x16x32_bf16 v[78:81], v[138:141], v[170:173], v[78:81]
	v_mfma_f32_16x16x32_bf16 v[70:73], v[130:133], v[162:165], v[70:73]
	v_mfma_f32_16x16x32_bf16 v[66:69], v[138:141], v[162:165], v[66:69]
	v_mfma_f32_16x16x32_bf16 v[118:121], v[134:137], v[190:193], v[118:121]
	v_mfma_f32_16x16x32_bf16 v[110:113], v[142:145], v[190:193], v[110:113]
	v_mfma_f32_16x16x32_bf16 v[102:105], v[134:137], v[182:185], v[102:105]
	v_mfma_f32_16x16x32_bf16 v[94:97], v[142:145], v[182:185], v[94:97]
	v_mfma_f32_16x16x32_bf16 v[86:89], v[134:137], v[174:177], v[86:89]
	v_mfma_f32_16x16x32_bf16 v[78:81], v[142:145], v[174:177], v[78:81]
	v_mfma_f32_16x16x32_bf16 v[70:73], v[134:137], v[166:169], v[70:73]
	v_mfma_f32_16x16x32_bf16 v[66:69], v[142:145], v[166:169], v[66:69]
	s_setprio 0
	s_barrier
	s_mov_b32 m0, s44
	s_or_b32 s31, s16, 0x100
	s_mov_b32 s66, s6
	s_mov_b32 s67, s7
	ds_read_b128 v[162:165], v204 offset:16384
	ds_read_b128 v[166:169], v204 offset:17408
	ds_read_b128 v[170:173], v204 offset:18432
	ds_read_b128 v[174:177], v204 offset:19456
	ds_read_b128 v[178:181], v204 offset:20480
	ds_read_b128 v[182:185], v204 offset:21504
	ds_read_b128 v[186:189], v204 offset:22528
	ds_read_b128 v[190:193], v204 offset:23552
	buffer_load_dwordx4 v195, s[64:67], s31 offen lds
	s_mov_b32 m0, s45
	s_nop 0
	buffer_load_dwordx4 v200, s[64:67], s31 offen lds
	s_or_b32 s31, s16, 0x80100
	s_mov_b32 m0, s41
	s_nop 0
	buffer_load_dwordx4 v195, s[64:67], s31 offen lds
	s_mov_b32 m0, s46
	s_nop 0
	buffer_load_dwordx4 v200, s[64:67], s31 offen lds
	s_or_b32 s31, s18, 0x100
	s_mov_b32 m0, s43
	s_nop 0
	buffer_load_dwordx4 v195, s[4:7], s31 offen lds
	s_mov_b32 m0, s15
	s_nop 0
	buffer_load_dwordx4 v200, s[4:7], s31 offen lds
	s_waitcnt vmcnt(8)
	s_waitcnt lgkmcnt(0)
	s_setprio 1
	s_barrier
	v_mfma_f32_16x16x32_bf16 v[62:65], v[146:149], v[162:165], v[62:65]
	v_mfma_f32_16x16x32_bf16 v[58:61], v[154:157], v[162:165], v[58:61]
	v_mfma_f32_16x16x32_bf16 v[46:49], v[146:149], v[170:173], v[46:49]
	v_mfma_f32_16x16x32_bf16 v[42:45], v[154:157], v[170:173], v[42:45]
	v_mfma_f32_16x16x32_bf16 v[34:37], v[146:149], v[178:181], v[34:37]
	v_mfma_f32_16x16x32_bf16 v[26:29], v[154:157], v[178:181], v[26:29]
	v_mfma_f32_16x16x32_bf16 v[18:21], v[146:149], v[186:189], v[18:21]
	v_mfma_f32_16x16x32_bf16 v[10:13], v[154:157], v[186:189], v[10:13]
	v_mfma_f32_16x16x32_bf16 v[62:65], v[150:153], v[166:169], v[62:65]
	v_mfma_f32_16x16x32_bf16 v[58:61], v[158:161], v[166:169], v[58:61]
	v_mfma_f32_16x16x32_bf16 v[46:49], v[150:153], v[174:177], v[46:49]
	v_mfma_f32_16x16x32_bf16 v[42:45], v[158:161], v[174:177], v[42:45]
	v_mfma_f32_16x16x32_bf16 v[34:37], v[150:153], v[182:185], v[34:37]
	v_mfma_f32_16x16x32_bf16 v[26:29], v[158:161], v[182:185], v[26:29]
	v_mfma_f32_16x16x32_bf16 v[18:21], v[150:153], v[190:193], v[18:21]
	v_mfma_f32_16x16x32_bf16 v[10:13], v[158:161], v[190:193], v[10:13]
	v_mfma_f32_16x16x32_bf16 v[54:57], v[130:133], v[162:165], v[54:57]
	v_mfma_f32_16x16x32_bf16 v[50:53], v[138:141], v[162:165], v[50:53]
	v_mfma_f32_16x16x32_bf16 v[38:41], v[130:133], v[170:173], v[38:41]
	v_mfma_f32_16x16x32_bf16 v[30:33], v[138:141], v[170:173], v[30:33]
	v_mfma_f32_16x16x32_bf16 v[22:25], v[130:133], v[178:181], v[22:25]
	v_mfma_f32_16x16x32_bf16 v[14:17], v[138:141], v[178:181], v[14:17]
	v_mfma_f32_16x16x32_bf16 v[6:9], v[130:133], v[186:189], v[6:9]
	v_mfma_f32_16x16x32_bf16 v[2:5], v[138:141], v[186:189], v[2:5]
	v_mfma_f32_16x16x32_bf16 v[54:57], v[134:137], v[166:169], v[54:57]
	v_mfma_f32_16x16x32_bf16 v[50:53], v[142:145], v[166:169], v[50:53]
	v_mfma_f32_16x16x32_bf16 v[38:41], v[134:137], v[174:177], v[38:41]
	v_mfma_f32_16x16x32_bf16 v[30:33], v[142:145], v[174:177], v[30:33]
	v_mfma_f32_16x16x32_bf16 v[22:25], v[134:137], v[182:185], v[22:25]
	v_mfma_f32_16x16x32_bf16 v[14:17], v[142:145], v[182:185], v[14:17]
	v_mfma_f32_16x16x32_bf16 v[6:9], v[134:137], v[190:193], v[6:9]
	v_mfma_f32_16x16x32_bf16 v[2:5], v[142:145], v[190:193], v[2:5]
	s_setprio 0
	s_barrier
; #define PG8_STAGEA(bufoff, goff, voff) PG8_STAGEX(rsA, bufoff, goff, voff)
; #define PG8_STAGEB(bufoff, goff, voff) PG8_STAGEX(rsB, bufoff, goff, voff)
; #define PG8_LDA(dst, b, h) do { _Pragma("unroll") for (int m = 0; m < 4; ++m) _Pragma("unroll") for (int k = 0; k < 2; ++k) dst[m][k] = *(const PG8_LAS bf16x8*)(lds + PG8_SA(b, h) + aoff + m * 2048 + k * 1024); } while (0)
; #define PG8_LDB(dst, b, h) do { _Pragma("unroll") for (int n = 0; n < 2; ++n) _Pragma("unroll") for (int k = 0; k < 2; ++k) dst[n][k] = *(const PG8_LAS bf16x8*)(lds + PG8_SB(b, h) + boff + n * 2048 + k * 1024); } while (0)
; #define PG8_MMA(ai, bj, At, Bt) do { __builtin_amdgcn_s_setprio(1); _Pragma("unroll") for (int m = 0; m < 4; ++m) _Pragma("unroll") for (int n = 0; n < 2; ++n) _Pragma("unroll") for (int k = 0; k < 2; ++k) \
;         acc[ai][bj][m][n] = __builtin_amdgcn_mfma_f32_16x16x32_bf16(Bt[n][k], At[m][k], acc[ai][bj][m][n], 0, 0, 0); __builtin_amdgcn_s_setprio(0); } while (0)
; #define PG8_WAIT_V(n) asm volatile("s_waitcnt vmcnt(" #n ")" ::: "memory")
; #define PG8_WAIT_L(n) asm volatile("s_waitcnt lgkmcnt(" #n ")" ::: "memory")
; #define PG8_BAR __builtin_amdgcn_s_barrier()
; #define PG8_SCHED __builtin_amdgcn_sched_barrier(0)
; template <class Epi, class Sched, bool ALIGN_EPI = false, bool SP2 = false>
; __device__ __forceinline__ void gemm_phase(PG8_LAS unsigned char* lds, const Gemm g, const Sched& S, const Epi& E) {
;     ...
;             PG8_LDB(B0, 1, 0); PG8_LDB(B1, 1, 1); PG8_SCHED; PG8_LDA(At, 1, 0); PG8_STAGEA(PG8_SA(0, 1), a2 + hstep, voffA);
;             PG8_WAIT_V(8); PG8_WAIT_L(0); PG8_BAR; PG8_MMA(0, 0, At, B0); PG8_MMA(0, 1, At, B1); PG8_BAR; PG8_SCHED;
;             PG8_LDA(At, 1, 1); PG8_STAGEB(PG8_SB(1, 0), b3, voffB); PG8_STAGEB(PG8_SB(1, 1), b3 + hstep, voffB); PG8_STAGEA(PG8_SA(1, 0), a3, voffA);
;             PG8_WAIT_V(8); PG8_WAIT_L(0); PG8_BAR; PG8_MMA(1, 0, At, B0); PG8_MMA(1, 1, At, B1); PG8_BAR; PG8_SCHED;
	v_add_u32_e32 v130, 0x18000, v203
	v_add_u32_e32 v131, 0x1c000, v203
	ds_read_b128 v[132:135], v130
	ds_read_b128 v[136:139], v130 offset:1024
	ds_read_b128 v[140:143], v130 offset:2048
	ds_read_b128 v[144:147], v130 offset:3072
	ds_read_b128 v[148:151], v131
	ds_read_b128 v[152:155], v131 offset:1024
	ds_read_b128 v[156:159], v131 offset:2048
	ds_read_b128 v[160:163], v131 offset:3072
	s_or_b32 s31, s18, 0x80100
	s_mov_b32 m0, s47
	ds_read_b128 v[164:167], v204 offset:32768
	ds_read_b128 v[168:171], v204 offset:33792
	ds_read_b128 v[172:175], v204 offset:34816
	ds_read_b128 v[176:179], v204 offset:35840
	ds_read_b128 v[180:183], v204 offset:36864
	ds_read_b128 v[184:187], v204 offset:37888
	ds_read_b128 v[188:191], v204 offset:38912
	ds_read_b128 v[208:211], v204 offset:39936
	buffer_load_dwordx4 v195, s[4:7], s31 offen lds
	s_mov_b32 m0, s48
	s_nop 0
	buffer_load_dwordx4 v200, s[4:7], s31 offen lds
	s_waitcnt vmcnt(8)
	s_waitcnt lgkmcnt(0)
	s_setprio 1
	s_barrier
	v_mfma_f32_16x16x32_bf16 v[126:129], v[132:135], v[164:167], v[126:129]
	v_mfma_f32_16x16x32_bf16 v[122:125], v[140:143], v[164:167], v[122:125]
	v_mfma_f32_16x16x32_bf16 v[114:117], v[132:135], v[172:175], v[114:117]
	v_mfma_f32_16x16x32_bf16 v[106:109], v[140:143], v[172:175], v[106:109]
	v_mfma_f32_16x16x32_bf16 v[98:101], v[132:135], v[180:183], v[98:101]
	v_mfma_f32_16x16x32_bf16 v[90:93], v[140:143], v[180:183], v[90:93]
	v_mfma_f32_16x16x32_bf16 v[82:85], v[132:135], v[188:191], v[82:85]
	v_mfma_f32_16x16x32_bf16 v[74:77], v[140:143], v[188:191], v[74:77]
	v_mfma_f32_16x16x32_bf16 v[126:129], v[136:139], v[168:171], v[126:129]
	v_mfma_f32_16x16x32_bf16 v[122:125], v[144:147], v[168:171], v[122:125]
	v_mfma_f32_16x16x32_bf16 v[114:117], v[136:139], v[176:179], v[114:117]
	v_mfma_f32_16x16x32_bf16 v[106:109], v[144:147], v[176:179], v[106:109]
	v_mfma_f32_16x16x32_bf16 v[98:101], v[136:139], v[184:187], v[98:101]
	v_mfma_f32_16x16x32_bf16 v[90:93], v[144:147], v[184:187], v[90:93]
	v_mfma_f32_16x16x32_bf16 v[82:85], v[136:139], v[208:211], v[82:85]
	v_mfma_f32_16x16x32_bf16 v[74:77], v[144:147], v[208:211], v[74:77]
	v_mfma_f32_16x16x32_bf16 v[118:121], v[148:151], v[164:167], v[118:121]
	v_mfma_f32_16x16x32_bf16 v[110:113], v[156:159], v[164:167], v[110:113]
	v_mfma_f32_16x16x32_bf16 v[102:105], v[148:151], v[172:175], v[102:105]
	v_mfma_f32_16x16x32_bf16 v[94:97], v[156:159], v[172:175], v[94:97]
	v_mfma_f32_16x16x32_bf16 v[86:89], v[148:151], v[180:183], v[86:89]
	v_mfma_f32_16x16x32_bf16 v[78:81], v[156:159], v[180:183], v[78:81]
	v_mfma_f32_16x16x32_bf16 v[70:73], v[148:151], v[188:191], v[70:73]
	v_mfma_f32_16x16x32_bf16 v[66:69], v[156:159], v[188:191], v[66:69]
	v_mfma_f32_16x16x32_bf16 v[118:121], v[152:155], v[168:171], v[118:121]
	v_mfma_f32_16x16x32_bf16 v[110:113], v[160:163], v[168:171], v[110:113]
	v_mfma_f32_16x16x32_bf16 v[102:105], v[152:155], v[176:179], v[102:105]
	v_mfma_f32_16x16x32_bf16 v[94:97], v[160:163], v[176:179], v[94:97]
	v_mfma_f32_16x16x32_bf16 v[86:89], v[152:155], v[184:187], v[86:89]
	v_mfma_f32_16x16x32_bf16 v[78:81], v[160:163], v[184:187], v[78:81]
	v_mfma_f32_16x16x32_bf16 v[70:73], v[152:155], v[208:211], v[70:73]
	v_mfma_f32_16x16x32_bf16 v[66:69], v[160:163], v[208:211], v[66:69]
	s_setprio 0
	s_barrier
	s_mov_b32 m0, s49
	s_or_b32 s31, s16, 0x180
	ds_read_b128 v[164:167], v204 offset:49152
	ds_read_b128 v[168:171], v204 offset:50176
	ds_read_b128 v[172:175], v204 offset:51200
	ds_read_b128 v[176:179], v204 offset:52224
	ds_read_b128 v[180:183], v204 offset:53248
	ds_read_b128 v[184:187], v204 offset:54272
	ds_read_b128 v[188:191], v204 offset:55296
	ds_read_b128 v[208:211], v204 offset:56320
	buffer_load_dwordx4 v195, s[64:67], s31 offen lds
	s_mov_b32 m0, s50
	s_nop 0
	buffer_load_dwordx4 v200, s[64:67], s31 offen lds
	s_or_b32 s31, s16, 0x80180
	s_mov_b32 m0, s57
	s_nop 0
	buffer_load_dwordx4 v195, s[64:67], s31 offen lds
	s_mov_b32 m0, s58
	s_nop 0
	buffer_load_dwordx4 v200, s[64:67], s31 offen lds
	s_or_b32 s31, s18, 0x180
	s_mov_b32 m0, s51
	s_nop 0
	buffer_load_dwordx4 v195, s[4:7], s31 offen lds
	s_mov_b32 m0, s56
	s_nop 0
	buffer_load_dwordx4 v200, s[4:7], s31 offen lds
	s_waitcnt vmcnt(8)
	s_waitcnt lgkmcnt(0)
	s_setprio 1
	s_barrier
	v_mfma_f32_16x16x32_bf16 v[62:65], v[132:135], v[164:167], v[62:65]
	v_mfma_f32_16x16x32_bf16 v[58:61], v[140:143], v[164:167], v[58:61]
	v_mfma_f32_16x16x32_bf16 v[46:49], v[132:135], v[172:175], v[46:49]
	v_mfma_f32_16x16x32_bf16 v[42:45], v[140:143], v[172:175], v[42:45]
	v_mfma_f32_16x16x32_bf16 v[34:37], v[132:135], v[180:183], v[34:37]
	v_mfma_f32_16x16x32_bf16 v[26:29], v[140:143], v[180:183], v[26:29]
	v_mfma_f32_16x16x32_bf16 v[18:21], v[132:135], v[188:191], v[18:21]
	v_mfma_f32_16x16x32_bf16 v[10:13], v[140:143], v[188:191], v[10:13]
	v_mfma_f32_16x16x32_bf16 v[62:65], v[136:139], v[168:171], v[62:65]
	v_mfma_f32_16x16x32_bf16 v[58:61], v[144:147], v[168:171], v[58:61]
	v_mfma_f32_16x16x32_bf16 v[46:49], v[136:139], v[176:179], v[46:49]
	v_mfma_f32_16x16x32_bf16 v[42:45], v[144:147], v[176:179], v[42:45]
	v_mfma_f32_16x16x32_bf16 v[34:37], v[136:139], v[184:187], v[34:37]
	v_mfma_f32_16x16x32_bf16 v[26:29], v[144:147], v[184:187], v[26:29]
	v_mfma_f32_16x16x32_bf16 v[18:21], v[136:139], v[208:211], v[18:21]
	v_mfma_f32_16x16x32_bf16 v[10:13], v[144:147], v[208:211], v[10:13]
	v_mfma_f32_16x16x32_bf16 v[54:57], v[148:151], v[164:167], v[54:57]
	v_mfma_f32_16x16x32_bf16 v[50:53], v[156:159], v[164:167], v[50:53]
	v_mfma_f32_16x16x32_bf16 v[38:41], v[148:151], v[172:175], v[38:41]
	v_mfma_f32_16x16x32_bf16 v[30:33], v[156:159], v[172:175], v[30:33]
	v_mfma_f32_16x16x32_bf16 v[22:25], v[148:151], v[180:183], v[22:25]
	v_mfma_f32_16x16x32_bf16 v[14:17], v[156:159], v[180:183], v[14:17]
	v_mfma_f32_16x16x32_bf16 v[6:9], v[148:151], v[188:191], v[6:9]
	v_mfma_f32_16x16x32_bf16 v[2:5], v[156:159], v[188:191], v[2:5]
	v_mfma_f32_16x16x32_bf16 v[54:57], v[152:155], v[168:171], v[54:57]
	v_mfma_f32_16x16x32_bf16 v[50:53], v[160:163], v[168:171], v[50:53]
	v_mfma_f32_16x16x32_bf16 v[38:41], v[152:155], v[176:179], v[38:41]
	v_mfma_f32_16x16x32_bf16 v[30:33], v[160:163], v[176:179], v[30:33]
	v_mfma_f32_16x16x32_bf16 v[22:25], v[152:155], v[184:187], v[22:25]
	v_mfma_f32_16x16x32_bf16 v[14:17], v[160:163], v[184:187], v[14:17]
	v_mfma_f32_16x16x32_bf16 v[6:9], v[152:155], v[208:211], v[6:9]
	v_mfma_f32_16x16x32_bf16 v[2:5], v[160:163], v[208:211], v[2:5]
	s_setprio 0
	s_barrier
	s_add_u32 s31, s18, 0x200
	s_mov_b32 s62, 0
	s_mov_b64 s[38:39], 0
	s_branch .LBB0_678
; #define PG8_STAGEA(bufoff, goff, voff) PG8_STAGEX(rsA, bufoff, goff, voff)
; #define PG8_STAGEB(bufoff, goff, voff) PG8_STAGEX(rsB, bufoff, goff, voff)
; #define PG8_LDA(dst, b, h) do { _Pragma("unroll") for (int m = 0; m < 4; ++m) _Pragma("unroll") for (int k = 0; k < 2; ++k) dst[m][k] = *(const PG8_LAS bf16x8*)(lds + PG8_SA(b, h) + aoff + m * 2048 + k * 1024); } while (0)
; #define PG8_LDB(dst, b, h) do { _Pragma("unroll") for (int n = 0; n < 2; ++n) _Pragma("unroll") for (int k = 0; k < 2; ++k) dst[n][k] = *(const PG8_LAS bf16x8*)(lds + PG8_SB(b, h) + boff + n * 2048 + k * 1024); } while (0)
; #define PG8_MMA(ai, bj, At, Bt) do { __builtin_amdgcn_s_setprio(1); _Pragma("unroll") for (int m = 0; m < 4; ++m) _Pragma("unroll") for (int n = 0; n < 2; ++n) _Pragma("unroll") for (int k = 0; k < 2; ++k) \
;         acc[ai][bj][m][n] = __builtin_amdgcn_mfma_f32_16x16x32_bf16(Bt[n][k], At[m][k], acc[ai][bj][m][n], 0, 0, 0); __builtin_amdgcn_s_setprio(0); } while (0)
; #define PG8_WAIT_V(n) asm volatile("s_waitcnt vmcnt(" #n ")" ::: "memory")
; #define PG8_WAIT_L(n) asm volatile("s_waitcnt lgkmcnt(" #n ")" ::: "memory")
; #define PG8_BAR __builtin_amdgcn_s_barrier()
; #define PG8_SCHED __builtin_amdgcn_sched_barrier(0)
; template <class Epi, class Sched, bool ALIGN_EPI = false, bool SP2 = false>
; __device__ __forceinline__ void gemm_phase(PG8_LAS unsigned char* lds, const Gemm g, const Sched& S, const Epi& E) {
;     ...
;             PG8_LDB(B0, 0, 0); PG8_LDB(B1, 0, 1); PG8_SCHED; PG8_LDA(At, 0, 0); PG8_STAGEA(PG8_SA(1, 1), a1 + hstep, voffA);
;             if (t == 0 && ui > 0) {
; #pragma unroll
;                 for (int a = 0; a < 2; ++a)
; #pragma unroll
;                     for (int b = 0; b < 2; ++b)
; #pragma unroll
;                         for (int m = 0; m < 4; ++m)
; #pragma unroll
;                             for (int n = 0; n < 2; ++n) acc[a][b][m][n] = (f32x4){0.f, 0.f, 0.f, 0.f}; }
;             PG8_WAIT_V(8); PG8_WAIT_L(0); PG8_BAR; PG8_MMA(0, 0, At, B0); PG8_MMA(0, 1, At, B1); PG8_BAR; PG8_SCHED;
;             PG8_LDA(At, 0, 1); PG8_STAGEB(PG8_SB(0, 0), b2, voffB); PG8_STAGEB(PG8_SB(0, 1), b2 + hstep, voffB); PG8_STAGEA(PG8_SA(0, 0), a2, voffA);
;             PG8_WAIT_V(8); PG8_WAIT_L(0); PG8_BAR; PG8_MMA(1, 0, At, B0); PG8_MMA(1, 1, At, B1); PG8_BAR; PG8_SCHED;
.LBB0_677:
	ds_read_b128 v[132:135], v205
	ds_read_b128 v[136:139], v205 offset:1024
	ds_read_b128 v[140:143], v205 offset:2048
	ds_read_b128 v[144:147], v205 offset:3072
	ds_read_b128 v[148:151], v206
	ds_read_b128 v[152:155], v206 offset:1024
	ds_read_b128 v[156:159], v206 offset:2048
	ds_read_b128 v[160:163], v206 offset:3072
	s_add_i32 s63, s18, s38
	s_add_i32 s63, s63, 0x80180
	s_add_i32 s66, s23, s38
	s_add_i32 s68, s31, s38
	s_cmpk_eq_i32 s38, 0xe00
	s_mov_b32 m0, s59
	ds_read_b128 v[164:167], v204
	ds_read_b128 v[168:171], v204 offset:1024
	ds_read_b128 v[172:175], v204 offset:2048
	ds_read_b128 v[176:179], v204 offset:3072
	ds_read_b128 v[180:183], v204 offset:4096
	ds_read_b128 v[184:187], v204 offset:5120
	ds_read_b128 v[188:191], v204 offset:6144
	ds_read_b128 v[208:211], v204 offset:7168
	buffer_load_dwordx4 v195, s[4:7], s63 offen lds
	s_mov_b32 m0, s61
	s_nop 0
	buffer_load_dwordx4 v200, s[4:7], s63 offen lds
	s_waitcnt vmcnt(8)
	s_waitcnt lgkmcnt(0)
	s_setprio 1
	s_barrier
	v_mfma_f32_16x16x32_bf16 v[126:129], v[132:135], v[164:167], v[126:129]
	v_mfma_f32_16x16x32_bf16 v[122:125], v[140:143], v[164:167], v[122:125]
	v_mfma_f32_16x16x32_bf16 v[114:117], v[132:135], v[172:175], v[114:117]
	v_mfma_f32_16x16x32_bf16 v[106:109], v[140:143], v[172:175], v[106:109]
	v_mfma_f32_16x16x32_bf16 v[98:101], v[132:135], v[180:183], v[98:101]
	v_mfma_f32_16x16x32_bf16 v[90:93], v[140:143], v[180:183], v[90:93]
	v_mfma_f32_16x16x32_bf16 v[82:85], v[132:135], v[188:191], v[82:85]
	v_mfma_f32_16x16x32_bf16 v[74:77], v[140:143], v[188:191], v[74:77]
	v_mfma_f32_16x16x32_bf16 v[126:129], v[136:139], v[168:171], v[126:129]
	v_mfma_f32_16x16x32_bf16 v[122:125], v[144:147], v[168:171], v[122:125]
	v_mfma_f32_16x16x32_bf16 v[114:117], v[136:139], v[176:179], v[114:117]
	v_mfma_f32_16x16x32_bf16 v[106:109], v[144:147], v[176:179], v[106:109]
	v_mfma_f32_16x16x32_bf16 v[98:101], v[136:139], v[184:187], v[98:101]
	v_mfma_f32_16x16x32_bf16 v[90:93], v[144:147], v[184:187], v[90:93]
	v_mfma_f32_16x16x32_bf16 v[82:85], v[136:139], v[208:211], v[82:85]
	v_mfma_f32_16x16x32_bf16 v[74:77], v[144:147], v[208:211], v[74:77]
	v_mfma_f32_16x16x32_bf16 v[118:121], v[148:151], v[164:167], v[118:121]
	v_mfma_f32_16x16x32_bf16 v[110:113], v[156:159], v[164:167], v[110:113]
	v_mfma_f32_16x16x32_bf16 v[102:105], v[148:151], v[172:175], v[102:105]
	v_mfma_f32_16x16x32_bf16 v[94:97], v[156:159], v[172:175], v[94:97]
	v_mfma_f32_16x16x32_bf16 v[86:89], v[148:151], v[180:183], v[86:89]
	v_mfma_f32_16x16x32_bf16 v[78:81], v[156:159], v[180:183], v[78:81]
	v_mfma_f32_16x16x32_bf16 v[70:73], v[148:151], v[188:191], v[70:73]
	v_mfma_f32_16x16x32_bf16 v[66:69], v[156:159], v[188:191], v[66:69]
	v_mfma_f32_16x16x32_bf16 v[118:121], v[152:155], v[168:171], v[118:121]
	v_mfma_f32_16x16x32_bf16 v[110:113], v[160:163], v[168:171], v[110:113]
	v_mfma_f32_16x16x32_bf16 v[102:105], v[152:155], v[176:179], v[102:105]
	v_mfma_f32_16x16x32_bf16 v[94:97], v[160:163], v[176:179], v[94:97]
	v_mfma_f32_16x16x32_bf16 v[86:89], v[152:155], v[184:187], v[86:89]
	v_mfma_f32_16x16x32_bf16 v[78:81], v[160:163], v[184:187], v[78:81]
	v_mfma_f32_16x16x32_bf16 v[70:73], v[152:155], v[208:211], v[70:73]
	v_mfma_f32_16x16x32_bf16 v[66:69], v[160:163], v[208:211], v[66:69]
	s_setprio 0
	s_barrier
	s_mov_b32 m0, s44
	s_cselect_b32 s63, s21, s66
	s_mov_b32 s66, s6
	s_mov_b32 s67, s7
	ds_read_b128 v[164:167], v204 offset:16384
	ds_read_b128 v[168:171], v204 offset:17408
	ds_read_b128 v[172:175], v204 offset:18432
	ds_read_b128 v[176:179], v204 offset:19456
	ds_read_b128 v[180:183], v204 offset:20480
	ds_read_b128 v[184:187], v204 offset:21504
	ds_read_b128 v[188:191], v204 offset:22528
	ds_read_b128 v[208:211], v204 offset:23552
	buffer_load_dwordx4 v195, s[64:67], s63 offen lds
	s_mov_b32 m0, s45
	s_cselect_b32 s68, s19, s68
	buffer_load_dwordx4 v200, s[64:67], s63 offen lds
	s_add_i32 s69, s63, 0x80000
	s_mov_b32 m0, s41
	s_nop 0
	buffer_load_dwordx4 v195, s[64:67], s69 offen lds
	s_mov_b32 m0, s46
	s_nop 0
	buffer_load_dwordx4 v200, s[64:67], s69 offen lds
	s_mov_b32 m0, s43
	s_nop 0
	buffer_load_dwordx4 v195, s[4:7], s68 offen lds
	s_mov_b32 m0, s15
	s_nop 0
	buffer_load_dwordx4 v200, s[4:7], s68 offen lds
	s_waitcnt vmcnt(8)
	s_waitcnt lgkmcnt(0)
	s_setprio 1
	s_barrier
	v_mfma_f32_16x16x32_bf16 v[62:65], v[132:135], v[164:167], v[62:65]
	v_mfma_f32_16x16x32_bf16 v[58:61], v[140:143], v[164:167], v[58:61]
	v_mfma_f32_16x16x32_bf16 v[46:49], v[132:135], v[172:175], v[46:49]
	v_mfma_f32_16x16x32_bf16 v[42:45], v[140:143], v[172:175], v[42:45]
	v_mfma_f32_16x16x32_bf16 v[34:37], v[132:135], v[180:183], v[34:37]
	v_mfma_f32_16x16x32_bf16 v[26:29], v[140:143], v[180:183], v[26:29]
	v_mfma_f32_16x16x32_bf16 v[18:21], v[132:135], v[188:191], v[18:21]
	v_mfma_f32_16x16x32_bf16 v[10:13], v[140:143], v[188:191], v[10:13]
	v_mfma_f32_16x16x32_bf16 v[62:65], v[136:139], v[168:171], v[62:65]
	v_mfma_f32_16x16x32_bf16 v[58:61], v[144:147], v[168:171], v[58:61]
	v_mfma_f32_16x16x32_bf16 v[46:49], v[136:139], v[176:179], v[46:49]
	v_mfma_f32_16x16x32_bf16 v[42:45], v[144:147], v[176:179], v[42:45]
	v_mfma_f32_16x16x32_bf16 v[34:37], v[136:139], v[184:187], v[34:37]
	v_mfma_f32_16x16x32_bf16 v[26:29], v[144:147], v[184:187], v[26:29]
	v_mfma_f32_16x16x32_bf16 v[18:21], v[136:139], v[208:211], v[18:21]
	v_mfma_f32_16x16x32_bf16 v[10:13], v[144:147], v[208:211], v[10:13]
	v_mfma_f32_16x16x32_bf16 v[54:57], v[148:151], v[164:167], v[54:57]
	v_mfma_f32_16x16x32_bf16 v[50:53], v[156:159], v[164:167], v[50:53]
	v_mfma_f32_16x16x32_bf16 v[38:41], v[148:151], v[172:175], v[38:41]
	v_mfma_f32_16x16x32_bf16 v[30:33], v[156:159], v[172:175], v[30:33]
	v_mfma_f32_16x16x32_bf16 v[22:25], v[148:151], v[180:183], v[22:25]
	v_mfma_f32_16x16x32_bf16 v[14:17], v[156:159], v[180:183], v[14:17]
	v_mfma_f32_16x16x32_bf16 v[6:9], v[148:151], v[188:191], v[6:9]
	v_mfma_f32_16x16x32_bf16 v[2:5], v[156:159], v[188:191], v[2:5]
	v_mfma_f32_16x16x32_bf16 v[54:57], v[152:155], v[168:171], v[54:57]
	v_mfma_f32_16x16x32_bf16 v[50:53], v[160:163], v[168:171], v[50:53]
	v_mfma_f32_16x16x32_bf16 v[38:41], v[152:155], v[176:179], v[38:41]
	v_mfma_f32_16x16x32_bf16 v[30:33], v[160:163], v[176:179], v[30:33]
	v_mfma_f32_16x16x32_bf16 v[22:25], v[152:155], v[184:187], v[22:25]
	v_mfma_f32_16x16x32_bf16 v[14:17], v[160:163], v[184:187], v[14:17]
	v_mfma_f32_16x16x32_bf16 v[6:9], v[152:155], v[208:211], v[6:9]
	v_mfma_f32_16x16x32_bf16 v[2:5], v[160:163], v[208:211], v[2:5]
	s_setprio 0
	s_barrier
; #define PG8_STAGEA(bufoff, goff, voff) PG8_STAGEX(rsA, bufoff, goff, voff)
; #define PG8_STAGEB(bufoff, goff, voff) PG8_STAGEX(rsB, bufoff, goff, voff)
; #define PG8_LDA(dst, b, h) do { _Pragma("unroll") for (int m = 0; m < 4; ++m) _Pragma("unroll") for (int k = 0; k < 2; ++k) dst[m][k] = *(const PG8_LAS bf16x8*)(lds + PG8_SA(b, h) + aoff + m * 2048 + k * 1024); } while (0)
; #define PG8_LDB(dst, b, h) do { _Pragma("unroll") for (int n = 0; n < 2; ++n) _Pragma("unroll") for (int k = 0; k < 2; ++k) dst[n][k] = *(const PG8_LAS bf16x8*)(lds + PG8_SB(b, h) + boff + n * 2048 + k * 1024); } while (0)
; #define PG8_MMA(ai, bj, At, Bt) do { __builtin_amdgcn_s_setprio(1); _Pragma("unroll") for (int m = 0; m < 4; ++m) _Pragma("unroll") for (int n = 0; n < 2; ++n) _Pragma("unroll") for (int k = 0; k < 2; ++k) \
;         acc[ai][bj][m][n] = __builtin_amdgcn_mfma_f32_16x16x32_bf16(Bt[n][k], At[m][k], acc[ai][bj][m][n], 0, 0, 0); __builtin_amdgcn_s_setprio(0); } while (0)
; #define PG8_WAIT_V(n) asm volatile("s_waitcnt vmcnt(" #n ")" ::: "memory")
; #define PG8_WAIT_L(n) asm volatile("s_waitcnt lgkmcnt(" #n ")" ::: "memory")
; #define PG8_BAR __builtin_amdgcn_s_barrier()
; #define PG8_SCHED __builtin_amdgcn_sched_barrier(0)
; template <class Epi, class Sched, bool ALIGN_EPI = false, bool SP2 = false>
; __device__ __forceinline__ void gemm_phase(PG8_LAS unsigned char* lds, const Gemm g, const Sched& S, const Epi& E) {
;     ...
;             PG8_LDB(B0, 1, 0); PG8_LDB(B1, 1, 1); PG8_SCHED; PG8_LDA(At, 1, 0); PG8_STAGEA(PG8_SA(0, 1), a2 + hstep, voffA);
;             PG8_WAIT_V(8); PG8_WAIT_L(0); PG8_BAR; PG8_MMA(0, 0, At, B0); PG8_MMA(0, 1, At, B1); PG8_BAR; PG8_SCHED;
;             PG8_LDA(At, 1, 1); PG8_STAGEB(PG8_SB(1, 0), b3, voffB); PG8_STAGEB(PG8_SB(1, 1), b3 + hstep, voffB); PG8_STAGEA(PG8_SA(1, 0), a3, voffA);
;             PG8_WAIT_V(8); PG8_WAIT_L(0); PG8_BAR; PG8_MMA(1, 0, At, B0); PG8_MMA(1, 1, At, B1); PG8_BAR; PG8_SCHED;
	ds_read_b128 v[132:135], v130
	ds_read_b128 v[136:139], v130 offset:1024
	ds_read_b128 v[140:143], v130 offset:2048
	ds_read_b128 v[144:147], v130 offset:3072
	ds_read_b128 v[148:151], v131
	ds_read_b128 v[152:155], v131 offset:1024
	ds_read_b128 v[156:159], v131 offset:2048
	ds_read_b128 v[160:163], v131 offset:3072
	s_add_i32 s69, s68, 0x80000
	s_mov_b32 m0, s47
	ds_read_b128 v[164:167], v204 offset:32768
	ds_read_b128 v[168:171], v204 offset:33792
	ds_read_b128 v[172:175], v204 offset:34816
	ds_read_b128 v[176:179], v204 offset:35840
	ds_read_b128 v[180:183], v204 offset:36864
	ds_read_b128 v[184:187], v204 offset:37888
	ds_read_b128 v[188:191], v204 offset:38912
	ds_read_b128 v[208:211], v204 offset:39936
	buffer_load_dwordx4 v195, s[4:7], s69 offen lds
	s_mov_b32 m0, s48
	s_nop 0
	buffer_load_dwordx4 v200, s[4:7], s69 offen lds
	s_waitcnt vmcnt(8)
	s_waitcnt lgkmcnt(0)
	s_setprio 1
	s_barrier
	v_mfma_f32_16x16x32_bf16 v[126:129], v[132:135], v[164:167], v[126:129]
	v_mfma_f32_16x16x32_bf16 v[122:125], v[140:143], v[164:167], v[122:125]
	v_mfma_f32_16x16x32_bf16 v[114:117], v[132:135], v[172:175], v[114:117]
	v_mfma_f32_16x16x32_bf16 v[106:109], v[140:143], v[172:175], v[106:109]
	v_mfma_f32_16x16x32_bf16 v[98:101], v[132:135], v[180:183], v[98:101]
	v_mfma_f32_16x16x32_bf16 v[90:93], v[140:143], v[180:183], v[90:93]
	v_mfma_f32_16x16x32_bf16 v[82:85], v[132:135], v[188:191], v[82:85]
	v_mfma_f32_16x16x32_bf16 v[74:77], v[140:143], v[188:191], v[74:77]
	v_mfma_f32_16x16x32_bf16 v[126:129], v[136:139], v[168:171], v[126:129]
	v_mfma_f32_16x16x32_bf16 v[122:125], v[144:147], v[168:171], v[122:125]
	v_mfma_f32_16x16x32_bf16 v[114:117], v[136:139], v[176:179], v[114:117]
	v_mfma_f32_16x16x32_bf16 v[106:109], v[144:147], v[176:179], v[106:109]
	v_mfma_f32_16x16x32_bf16 v[98:101], v[136:139], v[184:187], v[98:101]
	v_mfma_f32_16x16x32_bf16 v[90:93], v[144:147], v[184:187], v[90:93]
	v_mfma_f32_16x16x32_bf16 v[82:85], v[136:139], v[208:211], v[82:85]
	v_mfma_f32_16x16x32_bf16 v[74:77], v[144:147], v[208:211], v[74:77]
	v_mfma_f32_16x16x32_bf16 v[118:121], v[148:151], v[164:167], v[118:121]
	v_mfma_f32_16x16x32_bf16 v[110:113], v[156:159], v[164:167], v[110:113]
	v_mfma_f32_16x16x32_bf16 v[102:105], v[148:151], v[172:175], v[102:105]
	v_mfma_f32_16x16x32_bf16 v[94:97], v[156:159], v[172:175], v[94:97]
	v_mfma_f32_16x16x32_bf16 v[86:89], v[148:151], v[180:183], v[86:89]
	v_mfma_f32_16x16x32_bf16 v[78:81], v[156:159], v[180:183], v[78:81]
	v_mfma_f32_16x16x32_bf16 v[70:73], v[148:151], v[188:191], v[70:73]
	v_mfma_f32_16x16x32_bf16 v[66:69], v[156:159], v[188:191], v[66:69]
	v_mfma_f32_16x16x32_bf16 v[118:121], v[152:155], v[168:171], v[118:121]
	v_mfma_f32_16x16x32_bf16 v[110:113], v[160:163], v[168:171], v[110:113]
	v_mfma_f32_16x16x32_bf16 v[102:105], v[152:155], v[176:179], v[102:105]
	v_mfma_f32_16x16x32_bf16 v[94:97], v[160:163], v[176:179], v[94:97]
	v_mfma_f32_16x16x32_bf16 v[86:89], v[152:155], v[184:187], v[86:89]
	v_mfma_f32_16x16x32_bf16 v[78:81], v[160:163], v[184:187], v[78:81]
	v_mfma_f32_16x16x32_bf16 v[70:73], v[152:155], v[208:211], v[70:73]
	v_mfma_f32_16x16x32_bf16 v[66:69], v[160:163], v[208:211], v[66:69]
	s_setprio 0
	s_barrier
	s_mov_b32 m0, s49
	s_add_i32 s69, s63, 0x80
	ds_read_b128 v[164:167], v204 offset:49152
	ds_read_b128 v[168:171], v204 offset:50176
	ds_read_b128 v[172:175], v204 offset:51200
	ds_read_b128 v[176:179], v204 offset:52224
	ds_read_b128 v[180:183], v204 offset:53248
	ds_read_b128 v[184:187], v204 offset:54272
	ds_read_b128 v[188:191], v204 offset:55296
	ds_read_b128 v[208:211], v204 offset:56320
	buffer_load_dwordx4 v195, s[64:67], s69 offen lds
	s_mov_b32 m0, s50
	s_add_i32 s63, s63, 0x80080
	buffer_load_dwordx4 v200, s[64:67], s69 offen lds
	s_mov_b32 m0, s57
	s_addk_i32 s68, 0x80
	buffer_load_dwordx4 v195, s[64:67], s63 offen lds
	s_mov_b32 m0, s58
	s_nop 0
	buffer_load_dwordx4 v200, s[64:67], s63 offen lds
	s_mov_b32 m0, s51
	s_nop 0
	buffer_load_dwordx4 v195, s[4:7], s68 offen lds
	s_mov_b32 m0, s56
	s_nop 0
	buffer_load_dwordx4 v200, s[4:7], s68 offen lds
	s_waitcnt vmcnt(8)
	s_waitcnt lgkmcnt(0)
	s_setprio 1
	s_barrier
	v_mfma_f32_16x16x32_bf16 v[62:65], v[132:135], v[164:167], v[62:65]
	v_mfma_f32_16x16x32_bf16 v[58:61], v[140:143], v[164:167], v[58:61]
	v_mfma_f32_16x16x32_bf16 v[46:49], v[132:135], v[172:175], v[46:49]
	v_mfma_f32_16x16x32_bf16 v[42:45], v[140:143], v[172:175], v[42:45]
	v_mfma_f32_16x16x32_bf16 v[34:37], v[132:135], v[180:183], v[34:37]
	v_mfma_f32_16x16x32_bf16 v[26:29], v[140:143], v[180:183], v[26:29]
	v_mfma_f32_16x16x32_bf16 v[18:21], v[132:135], v[188:191], v[18:21]
	v_mfma_f32_16x16x32_bf16 v[10:13], v[140:143], v[188:191], v[10:13]
	v_mfma_f32_16x16x32_bf16 v[62:65], v[136:139], v[168:171], v[62:65]
	v_mfma_f32_16x16x32_bf16 v[58:61], v[144:147], v[168:171], v[58:61]
	v_mfma_f32_16x16x32_bf16 v[46:49], v[136:139], v[176:179], v[46:49]
	v_mfma_f32_16x16x32_bf16 v[42:45], v[144:147], v[176:179], v[42:45]
	v_mfma_f32_16x16x32_bf16 v[34:37], v[136:139], v[184:187], v[34:37]
	v_mfma_f32_16x16x32_bf16 v[26:29], v[144:147], v[184:187], v[26:29]
	v_mfma_f32_16x16x32_bf16 v[18:21], v[136:139], v[208:211], v[18:21]
	v_mfma_f32_16x16x32_bf16 v[10:13], v[144:147], v[208:211], v[10:13]
	v_mfma_f32_16x16x32_bf16 v[54:57], v[148:151], v[164:167], v[54:57]
	v_mfma_f32_16x16x32_bf16 v[50:53], v[156:159], v[164:167], v[50:53]
	v_mfma_f32_16x16x32_bf16 v[38:41], v[148:151], v[172:175], v[38:41]
	v_mfma_f32_16x16x32_bf16 v[30:33], v[156:159], v[172:175], v[30:33]
	v_mfma_f32_16x16x32_bf16 v[22:25], v[148:151], v[180:183], v[22:25]
	v_mfma_f32_16x16x32_bf16 v[14:17], v[156:159], v[180:183], v[14:17]
	v_mfma_f32_16x16x32_bf16 v[6:9], v[148:151], v[188:191], v[6:9]
	v_mfma_f32_16x16x32_bf16 v[2:5], v[156:159], v[188:191], v[2:5]
	v_mfma_f32_16x16x32_bf16 v[54:57], v[152:155], v[168:171], v[54:57]
	v_mfma_f32_16x16x32_bf16 v[50:53], v[160:163], v[168:171], v[50:53]
	v_mfma_f32_16x16x32_bf16 v[38:41], v[152:155], v[176:179], v[38:41]
	v_mfma_f32_16x16x32_bf16 v[30:33], v[160:163], v[176:179], v[30:33]
	v_mfma_f32_16x16x32_bf16 v[22:25], v[152:155], v[184:187], v[22:25]
	v_mfma_f32_16x16x32_bf16 v[14:17], v[160:163], v[184:187], v[14:17]
	v_mfma_f32_16x16x32_bf16 v[6:9], v[152:155], v[208:211], v[6:9]
	v_mfma_f32_16x16x32_bf16 v[2:5], v[160:163], v[208:211], v[2:5]
	s_setprio 0
	s_barrier
	s_add_i32 s62, s62, 2
	s_add_u32 s38, s38, 0x100
	s_addc_u32 s39, s39, 0
	s_cmp_gt_u32 s62, 29
	s_cbranch_scc1 .LBB0_680

; #define PG8_STAGEA(bufoff, goff, voff) PG8_STAGEX(rsA, bufoff, goff, voff)
; #define PG8_STAGEB(bufoff, goff, voff) PG8_STAGEX(rsB, bufoff, goff, voff)
; #define PG8_LDA(dst, b, h) do { _Pragma("unroll") for (int m = 0; m < 4; ++m) _Pragma("unroll") for (int k = 0; k < 2; ++k) dst[m][k] = *(const PG8_LAS bf16x8*)(lds + PG8_SA(b, h) + aoff + m * 2048 + k * 1024); } while (0)
; #define PG8_MMA(ai, bj, At, Bt) do { __builtin_amdgcn_s_setprio(1); _Pragma("unroll") for (int m = 0; m < 4; ++m) _Pragma("unroll") for (int n = 0; n < 2; ++n) _Pragma("unroll") for (int k = 0; k < 2; ++k) \
;         acc[ai][bj][m][n] = __builtin_amdgcn_mfma_f32_16x16x32_bf16(Bt[n][k], At[m][k], acc[ai][bj][m][n], 0, 0, 0); __builtin_amdgcn_s_setprio(0); } while (0)
; #define PG8_WAIT_V(n) asm volatile("s_waitcnt vmcnt(" #n ")" ::: "memory")
; #define PG8_WAIT_L(n) asm volatile("s_waitcnt lgkmcnt(" #n ")" ::: "memory")
; #define PG8_BAR __builtin_amdgcn_s_barrier()
; #define PG8_SCHED __builtin_amdgcn_sched_barrier(0)
; template <class Epi, class Sched, bool ALIGN_EPI = false, bool SP2 = false>
; __device__ __forceinline__ void gemm_phase(PG8_LAS unsigned char* lds, const Gemm g, const Sched& S, const Epi& E) {
;     ...
;         const size_t nA = has_next ? (size_t)nxt.pm * tstep : cA; const size_t nB = has_next ? (size_t)nxt.pn * tstep : cB;
;         for (int t = 0; t < nt; t += 2) {
;             const bool last = (t == nt - 2);
;             if constexpr (Epi::MIDK) { if (t == (nt >> 1)) E.midk(acc, wr, fr, lds); }
;             const size_t a1 = cA + (size_t)(t + 1) * kstep;
;             const size_t a2 = last ? nA : cA + (size_t)(t + 2) * kstep; const size_t b2 = last ? nB : cB + (size_t)(t + 2) * kstep;
;     ...
;             PG8_WAIT_V(8); PG8_WAIT_L(0); PG8_BAR; PG8_MMA(0, 0, At, B0); PG8_MMA(0, 1, At, B1); PG8_BAR; PG8_SCHED;
;             PG8_LDA(At, 0, 1); PG8_STAGEB(PG8_SB(0, 0), b2, voffB); PG8_STAGEB(PG8_SB(0, 1), b2 + hstep, voffB); PG8_STAGEA(PG8_SA(0, 0), a2, voffA);
;             PG8_WAIT_V(8); PG8_WAIT_L(0); PG8_BAR; PG8_MMA(1, 0, At, B0); PG8_MMA(1, 1, At, B1); PG8_BAR; PG8_SCHED;
.LBB0_788:
	s_ashr_i32 s35, s34, 31
	s_lshl_b64 s[36:37], s[34:35], 20
	s_and_b64 s[38:39], s[2:3], exec
	s_cselect_b32 s35, s36, s48
	s_ashr_i32 s31, s30, 31
	s_waitcnt vmcnt(8)
	s_lshl_b64 s[38:39], s[30:31], 20
	s_waitcnt lgkmcnt(0)
	s_and_b64 s[42:43], s[2:3], exec
	s_cselect_b32 s31, s38, s46
	s_setprio 1
	s_barrier
	v_mfma_f32_16x16x32_bf16 v[126:129], v[146:149], v[186:189], v[126:129]
	v_mfma_f32_16x16x32_bf16 v[122:125], v[154:157], v[186:189], v[122:125]
	v_mfma_f32_16x16x32_bf16 v[118:121], v[146:149], v[178:181], v[118:121]
	v_mfma_f32_16x16x32_bf16 v[114:117], v[154:157], v[178:181], v[114:117]
	v_mfma_f32_16x16x32_bf16 v[110:113], v[146:149], v[170:173], v[110:113]
	v_mfma_f32_16x16x32_bf16 v[106:109], v[154:157], v[170:173], v[106:109]
	v_mfma_f32_16x16x32_bf16 v[102:105], v[146:149], v[162:165], v[102:105]
	v_mfma_f32_16x16x32_bf16 v[98:101], v[154:157], v[162:165], v[98:101]
	v_mfma_f32_16x16x32_bf16 v[126:129], v[150:153], v[190:193], v[126:129]
	v_mfma_f32_16x16x32_bf16 v[122:125], v[158:161], v[190:193], v[122:125]
	v_mfma_f32_16x16x32_bf16 v[118:121], v[150:153], v[182:185], v[118:121]
	v_mfma_f32_16x16x32_bf16 v[114:117], v[158:161], v[182:185], v[114:117]
	v_mfma_f32_16x16x32_bf16 v[110:113], v[150:153], v[174:177], v[110:113]
	v_mfma_f32_16x16x32_bf16 v[106:109], v[158:161], v[174:177], v[106:109]
	v_mfma_f32_16x16x32_bf16 v[102:105], v[150:153], v[166:169], v[102:105]
	v_mfma_f32_16x16x32_bf16 v[98:101], v[158:161], v[166:169], v[98:101]
	v_mfma_f32_16x16x32_bf16 v[94:97], v[130:133], v[186:189], v[94:97]
	v_mfma_f32_16x16x32_bf16 v[90:93], v[138:141], v[186:189], v[90:93]
	v_mfma_f32_16x16x32_bf16 v[86:89], v[130:133], v[178:181], v[86:89]
	v_mfma_f32_16x16x32_bf16 v[82:85], v[138:141], v[178:181], v[82:85]
	v_mfma_f32_16x16x32_bf16 v[78:81], v[130:133], v[170:173], v[78:81]
	v_mfma_f32_16x16x32_bf16 v[74:77], v[138:141], v[170:173], v[74:77]
	v_mfma_f32_16x16x32_bf16 v[70:73], v[130:133], v[162:165], v[70:73]
	v_mfma_f32_16x16x32_bf16 v[66:69], v[138:141], v[162:165], v[66:69]
	v_mfma_f32_16x16x32_bf16 v[94:97], v[134:137], v[190:193], v[94:97]
	v_mfma_f32_16x16x32_bf16 v[90:93], v[142:145], v[190:193], v[90:93]
	v_mfma_f32_16x16x32_bf16 v[86:89], v[134:137], v[182:185], v[86:89]
	v_mfma_f32_16x16x32_bf16 v[82:85], v[142:145], v[182:185], v[82:85]
	v_mfma_f32_16x16x32_bf16 v[78:81], v[134:137], v[174:177], v[78:81]
	v_mfma_f32_16x16x32_bf16 v[74:77], v[142:145], v[174:177], v[74:77]
	v_mfma_f32_16x16x32_bf16 v[70:73], v[134:137], v[166:169], v[70:73]
	v_mfma_f32_16x16x32_bf16 v[66:69], v[142:145], v[166:169], v[66:69]
	s_setprio 0
	s_barrier
	s_mov_b32 m0, s57
	s_or_b32 s47, s46, 0x100
	s_mov_b32 s42, s62
	s_mov_b32 s43, s63
	ds_read_b128 v[162:165], v213 offset:16384
	ds_read_b128 v[166:169], v213 offset:17408
	ds_read_b128 v[170:173], v213 offset:18432
	ds_read_b128 v[174:177], v213 offset:19456
	ds_read_b128 v[178:181], v213 offset:20480
	ds_read_b128 v[182:185], v213 offset:21504
	ds_read_b128 v[186:189], v213 offset:22528
	ds_read_b128 v[190:193], v213 offset:23552
	buffer_load_dwordx4 v203, s[40:43], s47 offen lds
	s_mov_b32 m0, s58
	s_nop 0
	buffer_load_dwordx4 v205, s[40:43], s47 offen lds
	s_or_b32 s47, s46, 0x80100
	s_mov_b32 m0, s59
	s_nop 0
	buffer_load_dwordx4 v203, s[40:43], s47 offen lds
	s_mov_b32 m0, s64
	s_nop 0
	buffer_load_dwordx4 v205, s[40:43], s47 offen lds
	s_or_b32 s47, s48, 0x100
	s_mov_b32 m0, s56
	s_nop 0
	buffer_load_dwordx4 v202, s[60:63], s47 offen lds
	s_mov_b32 m0, s45
	s_nop 0
	buffer_load_dwordx4 v204, s[60:63], s47 offen lds
	s_waitcnt vmcnt(8)
	s_waitcnt lgkmcnt(0)
	s_setprio 1
	s_barrier
	v_mfma_f32_16x16x32_bf16 v[62:65], v[146:149], v[162:165], v[62:65]
	v_mfma_f32_16x16x32_bf16 v[58:61], v[154:157], v[162:165], v[58:61]
	v_mfma_f32_16x16x32_bf16 v[54:57], v[146:149], v[170:173], v[54:57]
	v_mfma_f32_16x16x32_bf16 v[50:53], v[154:157], v[170:173], v[50:53]
	v_mfma_f32_16x16x32_bf16 v[46:49], v[146:149], v[178:181], v[46:49]
	v_mfma_f32_16x16x32_bf16 v[42:45], v[154:157], v[178:181], v[42:45]
	v_mfma_f32_16x16x32_bf16 v[38:41], v[146:149], v[186:189], v[38:41]
	v_mfma_f32_16x16x32_bf16 v[34:37], v[154:157], v[186:189], v[34:37]
	v_mfma_f32_16x16x32_bf16 v[62:65], v[150:153], v[166:169], v[62:65]
	v_mfma_f32_16x16x32_bf16 v[58:61], v[158:161], v[166:169], v[58:61]
	v_mfma_f32_16x16x32_bf16 v[54:57], v[150:153], v[174:177], v[54:57]
	v_mfma_f32_16x16x32_bf16 v[50:53], v[158:161], v[174:177], v[50:53]
	v_mfma_f32_16x16x32_bf16 v[46:49], v[150:153], v[182:185], v[46:49]
	v_mfma_f32_16x16x32_bf16 v[42:45], v[158:161], v[182:185], v[42:45]
	v_mfma_f32_16x16x32_bf16 v[38:41], v[150:153], v[190:193], v[38:41]
	v_mfma_f32_16x16x32_bf16 v[34:37], v[158:161], v[190:193], v[34:37]
	v_mfma_f32_16x16x32_bf16 v[30:33], v[130:133], v[162:165], v[30:33]
	v_mfma_f32_16x16x32_bf16 v[26:29], v[138:141], v[162:165], v[26:29]
	v_mfma_f32_16x16x32_bf16 v[22:25], v[130:133], v[170:173], v[22:25]
	v_mfma_f32_16x16x32_bf16 v[18:21], v[138:141], v[170:173], v[18:21]
	v_mfma_f32_16x16x32_bf16 v[14:17], v[130:133], v[178:181], v[14:17]
	v_mfma_f32_16x16x32_bf16 v[10:13], v[138:141], v[178:181], v[10:13]
	v_mfma_f32_16x16x32_bf16 v[6:9], v[130:133], v[186:189], v[6:9]
	v_mfma_f32_16x16x32_bf16 v[2:5], v[138:141], v[186:189], v[2:5]
	v_mfma_f32_16x16x32_bf16 v[30:33], v[134:137], v[166:169], v[30:33]
	v_mfma_f32_16x16x32_bf16 v[26:29], v[142:145], v[166:169], v[26:29]
	v_mfma_f32_16x16x32_bf16 v[22:25], v[134:137], v[174:177], v[22:25]
	v_mfma_f32_16x16x32_bf16 v[18:21], v[142:145], v[174:177], v[18:21]
	v_mfma_f32_16x16x32_bf16 v[14:17], v[134:137], v[182:185], v[14:17]
	v_mfma_f32_16x16x32_bf16 v[10:13], v[142:145], v[182:185], v[10:13]
	v_mfma_f32_16x16x32_bf16 v[6:9], v[134:137], v[190:193], v[6:9]
	v_mfma_f32_16x16x32_bf16 v[2:5], v[142:145], v[190:193], v[2:5]
	s_setprio 0
	s_barrier
; #define PG8_STAGEA(bufoff, goff, voff) PG8_STAGEX(rsA, bufoff, goff, voff)
; #define PG8_STAGEB(bufoff, goff, voff) PG8_STAGEX(rsB, bufoff, goff, voff)
; #define PG8_LDA(dst, b, h) do { _Pragma("unroll") for (int m = 0; m < 4; ++m) _Pragma("unroll") for (int k = 0; k < 2; ++k) dst[m][k] = *(const PG8_LAS bf16x8*)(lds + PG8_SA(b, h) + aoff + m * 2048 + k * 1024); } while (0)
; #define PG8_LDB(dst, b, h) do { _Pragma("unroll") for (int n = 0; n < 2; ++n) _Pragma("unroll") for (int k = 0; k < 2; ++k) dst[n][k] = *(const PG8_LAS bf16x8*)(lds + PG8_SB(b, h) + boff + n * 2048 + k * 1024); } while (0)
; #define PG8_MMA(ai, bj, At, Bt) do { __builtin_amdgcn_s_setprio(1); _Pragma("unroll") for (int m = 0; m < 4; ++m) _Pragma("unroll") for (int n = 0; n < 2; ++n) _Pragma("unroll") for (int k = 0; k < 2; ++k) \
;         acc[ai][bj][m][n] = __builtin_amdgcn_mfma_f32_16x16x32_bf16(Bt[n][k], At[m][k], acc[ai][bj][m][n], 0, 0, 0); __builtin_amdgcn_s_setprio(0); } while (0)
; #define PG8_WAIT_V(n) asm volatile("s_waitcnt vmcnt(" #n ")" ::: "memory")
; #define PG8_WAIT_L(n) asm volatile("s_waitcnt lgkmcnt(" #n ")" ::: "memory")
; #define PG8_BAR __builtin_amdgcn_s_barrier()
; #define PG8_SCHED __builtin_amdgcn_sched_barrier(0)
; template <class Epi, class Sched, bool ALIGN_EPI = false, bool SP2 = false>
; __device__ __forceinline__ void gemm_phase(PG8_LAS unsigned char* lds, const Gemm g, const Sched& S, const Epi& E) {
;     ...
;             PG8_LDB(B0, 1, 0); PG8_LDB(B1, 1, 1); PG8_SCHED; PG8_LDA(At, 1, 0); PG8_STAGEA(PG8_SA(0, 1), a2 + hstep, voffA);
;             PG8_WAIT_V(8); PG8_WAIT_L(0); PG8_BAR; PG8_MMA(0, 0, At, B0); PG8_MMA(0, 1, At, B1); PG8_BAR; PG8_SCHED;
;             PG8_LDA(At, 1, 1); PG8_STAGEB(PG8_SB(1, 0), b3, voffB); PG8_STAGEB(PG8_SB(1, 1), b3 + hstep, voffB); PG8_STAGEA(PG8_SA(1, 0), a3, voffA);
;             PG8_WAIT_V(8); PG8_WAIT_L(0); PG8_BAR; PG8_MMA(1, 0, At, B0); PG8_MMA(1, 1, At, B1); PG8_BAR; PG8_SCHED;
	v_add_u32_e32 v130, 0x18000, v212
	v_add_u32_e32 v131, 0x1c000, v212
	ds_read_b128 v[132:135], v130
	ds_read_b128 v[136:139], v130 offset:1024
	ds_read_b128 v[140:143], v130 offset:2048
	ds_read_b128 v[144:147], v130 offset:3072
	ds_read_b128 v[148:151], v131
	ds_read_b128 v[152:155], v131 offset:1024
	ds_read_b128 v[156:159], v131 offset:2048
	ds_read_b128 v[160:163], v131 offset:3072
	s_or_b32 s47, s48, 0x80100
	s_mov_b32 m0, s65
	ds_read_b128 v[164:167], v213 offset:32768
	ds_read_b128 v[168:171], v213 offset:33792
	ds_read_b128 v[172:175], v213 offset:34816
	ds_read_b128 v[176:179], v213 offset:35840
	ds_read_b128 v[180:183], v213 offset:36864
	ds_read_b128 v[184:187], v213 offset:37888
	ds_read_b128 v[188:191], v213 offset:38912
	ds_read_b128 v[216:219], v213 offset:39936
	buffer_load_dwordx4 v202, s[60:63], s47 offen lds
	s_mov_b32 m0, s66
	s_nop 0
	buffer_load_dwordx4 v204, s[60:63], s47 offen lds
	s_waitcnt vmcnt(8)
	s_waitcnt lgkmcnt(0)
	s_setprio 1
	s_barrier
	v_mfma_f32_16x16x32_bf16 v[126:129], v[132:135], v[164:167], v[126:129]
	v_mfma_f32_16x16x32_bf16 v[122:125], v[140:143], v[164:167], v[122:125]
	v_mfma_f32_16x16x32_bf16 v[118:121], v[132:135], v[172:175], v[118:121]
	v_mfma_f32_16x16x32_bf16 v[114:117], v[140:143], v[172:175], v[114:117]
	v_mfma_f32_16x16x32_bf16 v[110:113], v[132:135], v[180:183], v[110:113]
	v_mfma_f32_16x16x32_bf16 v[106:109], v[140:143], v[180:183], v[106:109]
	v_mfma_f32_16x16x32_bf16 v[102:105], v[132:135], v[188:191], v[102:105]
	v_mfma_f32_16x16x32_bf16 v[98:101], v[140:143], v[188:191], v[98:101]
	v_mfma_f32_16x16x32_bf16 v[126:129], v[136:139], v[168:171], v[126:129]
	v_mfma_f32_16x16x32_bf16 v[122:125], v[144:147], v[168:171], v[122:125]
	v_mfma_f32_16x16x32_bf16 v[118:121], v[136:139], v[176:179], v[118:121]
	v_mfma_f32_16x16x32_bf16 v[114:117], v[144:147], v[176:179], v[114:117]
	v_mfma_f32_16x16x32_bf16 v[110:113], v[136:139], v[184:187], v[110:113]
	v_mfma_f32_16x16x32_bf16 v[106:109], v[144:147], v[184:187], v[106:109]
	v_mfma_f32_16x16x32_bf16 v[102:105], v[136:139], v[216:219], v[102:105]
	v_mfma_f32_16x16x32_bf16 v[98:101], v[144:147], v[216:219], v[98:101]
	v_mfma_f32_16x16x32_bf16 v[94:97], v[148:151], v[164:167], v[94:97]
	v_mfma_f32_16x16x32_bf16 v[90:93], v[156:159], v[164:167], v[90:93]
	v_mfma_f32_16x16x32_bf16 v[86:89], v[148:151], v[172:175], v[86:89]
	v_mfma_f32_16x16x32_bf16 v[82:85], v[156:159], v[172:175], v[82:85]
	v_mfma_f32_16x16x32_bf16 v[78:81], v[148:151], v[180:183], v[78:81]
	v_mfma_f32_16x16x32_bf16 v[74:77], v[156:159], v[180:183], v[74:77]
	v_mfma_f32_16x16x32_bf16 v[70:73], v[148:151], v[188:191], v[70:73]
	v_mfma_f32_16x16x32_bf16 v[66:69], v[156:159], v[188:191], v[66:69]
	v_mfma_f32_16x16x32_bf16 v[94:97], v[152:155], v[168:171], v[94:97]
	v_mfma_f32_16x16x32_bf16 v[90:93], v[160:163], v[168:171], v[90:93]
	v_mfma_f32_16x16x32_bf16 v[86:89], v[152:155], v[176:179], v[86:89]
	v_mfma_f32_16x16x32_bf16 v[82:85], v[160:163], v[176:179], v[82:85]
	v_mfma_f32_16x16x32_bf16 v[78:81], v[152:155], v[184:187], v[78:81]
	v_mfma_f32_16x16x32_bf16 v[74:77], v[160:163], v[184:187], v[74:77]
	v_mfma_f32_16x16x32_bf16 v[70:73], v[152:155], v[216:219], v[70:73]
	v_mfma_f32_16x16x32_bf16 v[66:69], v[160:163], v[216:219], v[66:69]
	s_setprio 0
	s_barrier
	s_mov_b32 m0, s67
	s_or_b32 s47, s46, 0x180
	ds_read_b128 v[164:167], v213 offset:49152
	ds_read_b128 v[168:171], v213 offset:50176
	ds_read_b128 v[172:175], v213 offset:51200
	ds_read_b128 v[176:179], v213 offset:52224
	ds_read_b128 v[180:183], v213 offset:53248
	ds_read_b128 v[184:187], v213 offset:54272
	ds_read_b128 v[188:191], v213 offset:55296
	ds_read_b128 v[216:219], v213 offset:56320
	buffer_load_dwordx4 v203, s[40:43], s47 offen lds
	s_mov_b32 m0, s68
	s_nop 0
	buffer_load_dwordx4 v205, s[40:43], s47 offen lds
	s_or_b32 s47, s46, 0x80180
	s_mov_b32 m0, s71
	s_nop 0
	buffer_load_dwordx4 v203, s[40:43], s47 offen lds
	s_mov_b32 m0, s72
	s_nop 0
	buffer_load_dwordx4 v205, s[40:43], s47 offen lds
	s_or_b32 s47, s48, 0x180
	s_mov_b32 m0, s69
	s_nop 0
	buffer_load_dwordx4 v202, s[60:63], s47 offen lds
	s_mov_b32 m0, s70
	s_nop 0
	buffer_load_dwordx4 v204, s[60:63], s47 offen lds
	s_waitcnt vmcnt(8)
	s_waitcnt lgkmcnt(0)
	s_setprio 1
	s_barrier
	v_mfma_f32_16x16x32_bf16 v[62:65], v[132:135], v[164:167], v[62:65]
	v_mfma_f32_16x16x32_bf16 v[58:61], v[140:143], v[164:167], v[58:61]
	v_mfma_f32_16x16x32_bf16 v[54:57], v[132:135], v[172:175], v[54:57]
	v_mfma_f32_16x16x32_bf16 v[50:53], v[140:143], v[172:175], v[50:53]
	v_mfma_f32_16x16x32_bf16 v[46:49], v[132:135], v[180:183], v[46:49]
	v_mfma_f32_16x16x32_bf16 v[42:45], v[140:143], v[180:183], v[42:45]
	v_mfma_f32_16x16x32_bf16 v[38:41], v[132:135], v[188:191], v[38:41]
	v_mfma_f32_16x16x32_bf16 v[34:37], v[140:143], v[188:191], v[34:37]
	v_mfma_f32_16x16x32_bf16 v[62:65], v[136:139], v[168:171], v[62:65]
	v_mfma_f32_16x16x32_bf16 v[58:61], v[144:147], v[168:171], v[58:61]
	v_mfma_f32_16x16x32_bf16 v[54:57], v[136:139], v[176:179], v[54:57]
	v_mfma_f32_16x16x32_bf16 v[50:53], v[144:147], v[176:179], v[50:53]
	v_mfma_f32_16x16x32_bf16 v[46:49], v[136:139], v[184:187], v[46:49]
	v_mfma_f32_16x16x32_bf16 v[42:45], v[144:147], v[184:187], v[42:45]
	v_mfma_f32_16x16x32_bf16 v[38:41], v[136:139], v[216:219], v[38:41]
	v_mfma_f32_16x16x32_bf16 v[34:37], v[144:147], v[216:219], v[34:37]
	v_mfma_f32_16x16x32_bf16 v[30:33], v[148:151], v[164:167], v[30:33]
	v_mfma_f32_16x16x32_bf16 v[26:29], v[156:159], v[164:167], v[26:29]
	v_mfma_f32_16x16x32_bf16 v[22:25], v[148:151], v[172:175], v[22:25]
	v_mfma_f32_16x16x32_bf16 v[18:21], v[156:159], v[172:175], v[18:21]
	v_mfma_f32_16x16x32_bf16 v[14:17], v[148:151], v[180:183], v[14:17]
	v_mfma_f32_16x16x32_bf16 v[10:13], v[156:159], v[180:183], v[10:13]
	v_mfma_f32_16x16x32_bf16 v[6:9], v[148:151], v[188:191], v[6:9]
	v_mfma_f32_16x16x32_bf16 v[2:5], v[156:159], v[188:191], v[2:5]
	v_mfma_f32_16x16x32_bf16 v[30:33], v[152:155], v[168:171], v[30:33]
	v_mfma_f32_16x16x32_bf16 v[26:29], v[160:163], v[168:171], v[26:29]
	v_mfma_f32_16x16x32_bf16 v[22:25], v[152:155], v[176:179], v[22:25]
	v_mfma_f32_16x16x32_bf16 v[18:21], v[160:163], v[176:179], v[18:21]
	v_mfma_f32_16x16x32_bf16 v[14:17], v[152:155], v[184:187], v[14:17]
	v_mfma_f32_16x16x32_bf16 v[10:13], v[160:163], v[184:187], v[10:13]
	v_mfma_f32_16x16x32_bf16 v[6:9], v[152:155], v[216:219], v[6:9]
	v_mfma_f32_16x16x32_bf16 v[2:5], v[160:163], v[216:219], v[2:5]
	s_setprio 0
	s_barrier
	s_add_u32 s48, s48, 0x200
	s_add_u32 s49, s46, 0x200
	s_mov_b32 s80, 0
	s_mov_b64 s[46:47], 0
; #define PG8_STAGEA(bufoff, goff, voff) PG8_STAGEX(rsA, bufoff, goff, voff)
; #define PG8_STAGEB(bufoff, goff, voff) PG8_STAGEX(rsB, bufoff, goff, voff)
; #define PG8_LDA(dst, b, h) do { _Pragma("unroll") for (int m = 0; m < 4; ++m) _Pragma("unroll") for (int k = 0; k < 2; ++k) dst[m][k] = *(const PG8_LAS bf16x8*)(lds + PG8_SA(b, h) + aoff + m * 2048 + k * 1024); } while (0)
; #define PG8_LDB(dst, b, h) do { _Pragma("unroll") for (int n = 0; n < 2; ++n) _Pragma("unroll") for (int k = 0; k < 2; ++k) dst[n][k] = *(const PG8_LAS bf16x8*)(lds + PG8_SB(b, h) + boff + n * 2048 + k * 1024); } while (0)
; #define PG8_MMA(ai, bj, At, Bt) do { __builtin_amdgcn_s_setprio(1); _Pragma("unroll") for (int m = 0; m < 4; ++m) _Pragma("unroll") for (int n = 0; n < 2; ++n) _Pragma("unroll") for (int k = 0; k < 2; ++k) \
;         acc[ai][bj][m][n] = __builtin_amdgcn_mfma_f32_16x16x32_bf16(Bt[n][k], At[m][k], acc[ai][bj][m][n], 0, 0, 0); __builtin_amdgcn_s_setprio(0); } while (0)
; #define PG8_WAIT_V(n) asm volatile("s_waitcnt vmcnt(" #n ")" ::: "memory")
; #define PG8_WAIT_L(n) asm volatile("s_waitcnt lgkmcnt(" #n ")" ::: "memory")
; #define PG8_BAR __builtin_amdgcn_s_barrier()
; #define PG8_SCHED __builtin_amdgcn_sched_barrier(0)
; template <class Epi, class Sched, bool ALIGN_EPI = false, bool SP2 = false>
; __device__ __forceinline__ void gemm_phase(PG8_LAS unsigned char* lds, const Gemm g, const Sched& S, const Epi& E) {
;     ...
;             PG8_LDB(B0, 0, 0); PG8_LDB(B1, 0, 1); PG8_SCHED; PG8_LDA(At, 0, 0); PG8_STAGEA(PG8_SA(1, 1), a1 + hstep, voffA);
;             if (t == 0 && ui > 0) {
; #pragma unroll
;                 for (int a = 0; a < 2; ++a)
; #pragma unroll
;                     for (int b = 0; b < 2; ++b)
; #pragma unroll
;                         for (int m = 0; m < 4; ++m)
; #pragma unroll
;                             for (int n = 0; n < 2; ++n) acc[a][b][m][n] = (f32x4){0.f, 0.f, 0.f, 0.f}; }
;             PG8_WAIT_V(8); PG8_WAIT_L(0); PG8_BAR; PG8_MMA(0, 0, At, B0); PG8_MMA(0, 1, At, B1); PG8_BAR; PG8_SCHED;
;             PG8_LDA(At, 0, 1); PG8_STAGEB(PG8_SB(0, 0), b2, voffB); PG8_STAGEB(PG8_SB(0, 1), b2 + hstep, voffB); PG8_STAGEA(PG8_SA(0, 0), a2, voffA);
;             PG8_WAIT_V(8); PG8_WAIT_L(0); PG8_BAR; PG8_MMA(1, 0, At, B0); PG8_MMA(1, 1, At, B1); PG8_BAR; PG8_SCHED;
.LBB0_789:
	ds_read_b128 v[132:135], v196
	ds_read_b128 v[136:139], v196 offset:1024
	ds_read_b128 v[140:143], v196 offset:2048
	ds_read_b128 v[144:147], v196 offset:3072
	ds_read_b128 v[148:151], v214
	ds_read_b128 v[152:155], v214 offset:1024
	ds_read_b128 v[156:159], v214 offset:2048
	ds_read_b128 v[160:163], v214 offset:3072
	s_add_i32 s81, s48, s46
	s_mov_b32 m0, s73
	s_add_i32 s82, s81, 0x7ff80
	ds_read_b128 v[164:167], v213
	ds_read_b128 v[168:171], v213 offset:1024
	ds_read_b128 v[172:175], v213 offset:2048
	ds_read_b128 v[176:179], v213 offset:3072
	ds_read_b128 v[180:183], v213 offset:4096
	ds_read_b128 v[184:187], v213 offset:5120
	ds_read_b128 v[188:191], v213 offset:6144
	ds_read_b128 v[216:219], v213 offset:7168
	buffer_load_dwordx4 v202, s[60:63], s82 offen lds
	s_mov_b32 m0, s74
	s_nop 0
	buffer_load_dwordx4 v204, s[60:63], s82 offen lds
	s_waitcnt vmcnt(8)
	s_waitcnt lgkmcnt(0)
	s_add_i32 s82, s49, s46
	s_cmp_eq_u32 s80, 28
	s_setprio 1
	s_barrier
	v_mfma_f32_16x16x32_bf16 v[126:129], v[132:135], v[164:167], v[126:129]
	v_mfma_f32_16x16x32_bf16 v[122:125], v[140:143], v[164:167], v[122:125]
	v_mfma_f32_16x16x32_bf16 v[118:121], v[132:135], v[172:175], v[118:121]
	v_mfma_f32_16x16x32_bf16 v[114:117], v[140:143], v[172:175], v[114:117]
	v_mfma_f32_16x16x32_bf16 v[110:113], v[132:135], v[180:183], v[110:113]
	v_mfma_f32_16x16x32_bf16 v[106:109], v[140:143], v[180:183], v[106:109]
	v_mfma_f32_16x16x32_bf16 v[102:105], v[132:135], v[188:191], v[102:105]
	v_mfma_f32_16x16x32_bf16 v[98:101], v[140:143], v[188:191], v[98:101]
	v_mfma_f32_16x16x32_bf16 v[126:129], v[136:139], v[168:171], v[126:129]
	v_mfma_f32_16x16x32_bf16 v[122:125], v[144:147], v[168:171], v[122:125]
	v_mfma_f32_16x16x32_bf16 v[118:121], v[136:139], v[176:179], v[118:121]
	v_mfma_f32_16x16x32_bf16 v[114:117], v[144:147], v[176:179], v[114:117]
	v_mfma_f32_16x16x32_bf16 v[110:113], v[136:139], v[184:187], v[110:113]
	v_mfma_f32_16x16x32_bf16 v[106:109], v[144:147], v[184:187], v[106:109]
	v_mfma_f32_16x16x32_bf16 v[102:105], v[136:139], v[216:219], v[102:105]
	v_mfma_f32_16x16x32_bf16 v[98:101], v[144:147], v[216:219], v[98:101]
	v_mfma_f32_16x16x32_bf16 v[94:97], v[148:151], v[164:167], v[94:97]
	v_mfma_f32_16x16x32_bf16 v[90:93], v[156:159], v[164:167], v[90:93]
	v_mfma_f32_16x16x32_bf16 v[86:89], v[148:151], v[172:175], v[86:89]
	v_mfma_f32_16x16x32_bf16 v[82:85], v[156:159], v[172:175], v[82:85]
	v_mfma_f32_16x16x32_bf16 v[78:81], v[148:151], v[180:183], v[78:81]
	v_mfma_f32_16x16x32_bf16 v[74:77], v[156:159], v[180:183], v[74:77]
	v_mfma_f32_16x16x32_bf16 v[70:73], v[148:151], v[188:191], v[70:73]
	v_mfma_f32_16x16x32_bf16 v[66:69], v[156:159], v[188:191], v[66:69]
	v_mfma_f32_16x16x32_bf16 v[94:97], v[152:155], v[168:171], v[94:97]
	v_mfma_f32_16x16x32_bf16 v[90:93], v[160:163], v[168:171], v[90:93]
	v_mfma_f32_16x16x32_bf16 v[86:89], v[152:155], v[176:179], v[86:89]
	v_mfma_f32_16x16x32_bf16 v[82:85], v[160:163], v[176:179], v[82:85]
	v_mfma_f32_16x16x32_bf16 v[78:81], v[152:155], v[184:187], v[78:81]
	v_mfma_f32_16x16x32_bf16 v[74:77], v[160:163], v[184:187], v[74:77]
	v_mfma_f32_16x16x32_bf16 v[70:73], v[152:155], v[216:219], v[70:73]
	v_mfma_f32_16x16x32_bf16 v[66:69], v[160:163], v[216:219], v[66:69]
	s_setprio 0
	s_barrier
	s_mov_b32 m0, s57
	s_cselect_b32 s82, s31, s82
	ds_read_b128 v[164:167], v213 offset:16384
	ds_read_b128 v[168:171], v213 offset:17408
	ds_read_b128 v[172:175], v213 offset:18432
	ds_read_b128 v[176:179], v213 offset:19456
	ds_read_b128 v[180:183], v213 offset:20480
	ds_read_b128 v[184:187], v213 offset:21504
	ds_read_b128 v[188:191], v213 offset:22528
	ds_read_b128 v[216:219], v213 offset:23552
	buffer_load_dwordx4 v203, s[40:43], s82 offen lds
	s_mov_b32 m0, s58
	s_cselect_b32 s81, s35, s81
	buffer_load_dwordx4 v205, s[40:43], s82 offen lds
	s_add_i32 s83, s82, 0x80000
	s_mov_b32 m0, s59
	s_nop 0
	buffer_load_dwordx4 v203, s[40:43], s83 offen lds
	s_mov_b32 m0, s64
	s_nop 0
	buffer_load_dwordx4 v205, s[40:43], s83 offen lds
	s_mov_b32 m0, s56
	s_nop 0
	buffer_load_dwordx4 v202, s[60:63], s81 offen lds
	s_mov_b32 m0, s45
	s_nop 0
	buffer_load_dwordx4 v204, s[60:63], s81 offen lds
	s_waitcnt vmcnt(8)
	s_waitcnt lgkmcnt(0)
	s_setprio 1
	s_barrier
	v_mfma_f32_16x16x32_bf16 v[62:65], v[132:135], v[164:167], v[62:65]
	v_mfma_f32_16x16x32_bf16 v[58:61], v[140:143], v[164:167], v[58:61]
	v_mfma_f32_16x16x32_bf16 v[54:57], v[132:135], v[172:175], v[54:57]
	v_mfma_f32_16x16x32_bf16 v[50:53], v[140:143], v[172:175], v[50:53]
	v_mfma_f32_16x16x32_bf16 v[46:49], v[132:135], v[180:183], v[46:49]
	v_mfma_f32_16x16x32_bf16 v[42:45], v[140:143], v[180:183], v[42:45]
	v_mfma_f32_16x16x32_bf16 v[38:41], v[132:135], v[188:191], v[38:41]
	v_mfma_f32_16x16x32_bf16 v[34:37], v[140:143], v[188:191], v[34:37]
	v_mfma_f32_16x16x32_bf16 v[62:65], v[136:139], v[168:171], v[62:65]
	v_mfma_f32_16x16x32_bf16 v[58:61], v[144:147], v[168:171], v[58:61]
	v_mfma_f32_16x16x32_bf16 v[54:57], v[136:139], v[176:179], v[54:57]
	v_mfma_f32_16x16x32_bf16 v[50:53], v[144:147], v[176:179], v[50:53]
	v_mfma_f32_16x16x32_bf16 v[46:49], v[136:139], v[184:187], v[46:49]
	v_mfma_f32_16x16x32_bf16 v[42:45], v[144:147], v[184:187], v[42:45]
	v_mfma_f32_16x16x32_bf16 v[38:41], v[136:139], v[216:219], v[38:41]
	v_mfma_f32_16x16x32_bf16 v[34:37], v[144:147], v[216:219], v[34:37]
	v_mfma_f32_16x16x32_bf16 v[30:33], v[148:151], v[164:167], v[30:33]
	v_mfma_f32_16x16x32_bf16 v[26:29], v[156:159], v[164:167], v[26:29]
	v_mfma_f32_16x16x32_bf16 v[22:25], v[148:151], v[172:175], v[22:25]
	v_mfma_f32_16x16x32_bf16 v[18:21], v[156:159], v[172:175], v[18:21]
	v_mfma_f32_16x16x32_bf16 v[14:17], v[148:151], v[180:183], v[14:17]
	v_mfma_f32_16x16x32_bf16 v[10:13], v[156:159], v[180:183], v[10:13]
	v_mfma_f32_16x16x32_bf16 v[6:9], v[148:151], v[188:191], v[6:9]
	v_mfma_f32_16x16x32_bf16 v[2:5], v[156:159], v[188:191], v[2:5]
	v_mfma_f32_16x16x32_bf16 v[30:33], v[152:155], v[168:171], v[30:33]
	v_mfma_f32_16x16x32_bf16 v[26:29], v[160:163], v[168:171], v[26:29]
	v_mfma_f32_16x16x32_bf16 v[22:25], v[152:155], v[176:179], v[22:25]
	v_mfma_f32_16x16x32_bf16 v[18:21], v[160:163], v[176:179], v[18:21]
	v_mfma_f32_16x16x32_bf16 v[14:17], v[152:155], v[184:187], v[14:17]
	v_mfma_f32_16x16x32_bf16 v[10:13], v[160:163], v[184:187], v[10:13]
	v_mfma_f32_16x16x32_bf16 v[6:9], v[152:155], v[216:219], v[6:9]
	v_mfma_f32_16x16x32_bf16 v[2:5], v[160:163], v[216:219], v[2:5]
	s_setprio 0
	s_barrier
; #define PG8_STAGEA(bufoff, goff, voff) PG8_STAGEX(rsA, bufoff, goff, voff)
; #define PG8_STAGEB(bufoff, goff, voff) PG8_STAGEX(rsB, bufoff, goff, voff)
; #define PG8_LDA(dst, b, h) do { _Pragma("unroll") for (int m = 0; m < 4; ++m) _Pragma("unroll") for (int k = 0; k < 2; ++k) dst[m][k] = *(const PG8_LAS bf16x8*)(lds + PG8_SA(b, h) + aoff + m * 2048 + k * 1024); } while (0)
; #define PG8_LDB(dst, b, h) do { _Pragma("unroll") for (int n = 0; n < 2; ++n) _Pragma("unroll") for (int k = 0; k < 2; ++k) dst[n][k] = *(const PG8_LAS bf16x8*)(lds + PG8_SB(b, h) + boff + n * 2048 + k * 1024); } while (0)
; #define PG8_MMA(ai, bj, At, Bt) do { __builtin_amdgcn_s_setprio(1); _Pragma("unroll") for (int m = 0; m < 4; ++m) _Pragma("unroll") for (int n = 0; n < 2; ++n) _Pragma("unroll") for (int k = 0; k < 2; ++k) \
;         acc[ai][bj][m][n] = __builtin_amdgcn_mfma_f32_16x16x32_bf16(Bt[n][k], At[m][k], acc[ai][bj][m][n], 0, 0, 0); __builtin_amdgcn_s_setprio(0); } while (0)
; #define PG8_WAIT_V(n) asm volatile("s_waitcnt vmcnt(" #n ")" ::: "memory")
; #define PG8_WAIT_L(n) asm volatile("s_waitcnt lgkmcnt(" #n ")" ::: "memory")
; #define PG8_BAR __builtin_amdgcn_s_barrier()
; #define PG8_SCHED __builtin_amdgcn_sched_barrier(0)
; template <class Epi, class Sched, bool ALIGN_EPI = false, bool SP2 = false>
; __device__ __forceinline__ void gemm_phase(PG8_LAS unsigned char* lds, const Gemm g, const Sched& S, const Epi& E) {
;     ...
;             PG8_LDB(B0, 1, 0); PG8_LDB(B1, 1, 1); PG8_SCHED; PG8_LDA(At, 1, 0); PG8_STAGEA(PG8_SA(0, 1), a2 + hstep, voffA);
;             PG8_WAIT_V(8); PG8_WAIT_L(0); PG8_BAR; PG8_MMA(0, 0, At, B0); PG8_MMA(0, 1, At, B1); PG8_BAR; PG8_SCHED;
;             PG8_LDA(At, 1, 1); PG8_STAGEB(PG8_SB(1, 0), b3, voffB); PG8_STAGEB(PG8_SB(1, 1), b3 + hstep, voffB); PG8_STAGEA(PG8_SA(1, 0), a3, voffA);
;             PG8_WAIT_V(8); PG8_WAIT_L(0); PG8_BAR; PG8_MMA(1, 0, At, B0); PG8_MMA(1, 1, At, B1); PG8_BAR; PG8_SCHED;
;     ...
;         if constexpr (ALIGN_EPI) { if (wr == 0) PG8_BAR; }
	ds_read_b128 v[132:135], v130
	ds_read_b128 v[136:139], v130 offset:1024
	ds_read_b128 v[140:143], v130 offset:2048
	ds_read_b128 v[144:147], v130 offset:3072
	ds_read_b128 v[148:151], v131
	ds_read_b128 v[152:155], v131 offset:1024
	ds_read_b128 v[156:159], v131 offset:2048
	ds_read_b128 v[160:163], v131 offset:3072
	s_add_i32 s83, s81, 0x80000
	s_mov_b32 m0, s65
	ds_read_b128 v[164:167], v213 offset:32768
	ds_read_b128 v[168:171], v213 offset:33792
	ds_read_b128 v[172:175], v213 offset:34816
	ds_read_b128 v[176:179], v213 offset:35840
	ds_read_b128 v[180:183], v213 offset:36864
	ds_read_b128 v[184:187], v213 offset:37888
	ds_read_b128 v[188:191], v213 offset:38912
	ds_read_b128 v[216:219], v213 offset:39936
	buffer_load_dwordx4 v202, s[60:63], s83 offen lds
	s_mov_b32 m0, s66
	s_nop 0
	buffer_load_dwordx4 v204, s[60:63], s83 offen lds
	s_waitcnt vmcnt(8)
	s_waitcnt lgkmcnt(0)
	s_setprio 1
	s_barrier
	v_mfma_f32_16x16x32_bf16 v[126:129], v[132:135], v[164:167], v[126:129]
	v_mfma_f32_16x16x32_bf16 v[122:125], v[140:143], v[164:167], v[122:125]
	v_mfma_f32_16x16x32_bf16 v[118:121], v[132:135], v[172:175], v[118:121]
	v_mfma_f32_16x16x32_bf16 v[114:117], v[140:143], v[172:175], v[114:117]
	v_mfma_f32_16x16x32_bf16 v[110:113], v[132:135], v[180:183], v[110:113]
	v_mfma_f32_16x16x32_bf16 v[106:109], v[140:143], v[180:183], v[106:109]
	v_mfma_f32_16x16x32_bf16 v[102:105], v[132:135], v[188:191], v[102:105]
	v_mfma_f32_16x16x32_bf16 v[98:101], v[140:143], v[188:191], v[98:101]
	v_mfma_f32_16x16x32_bf16 v[126:129], v[136:139], v[168:171], v[126:129]
	v_mfma_f32_16x16x32_bf16 v[122:125], v[144:147], v[168:171], v[122:125]
	v_mfma_f32_16x16x32_bf16 v[118:121], v[136:139], v[176:179], v[118:121]
	v_mfma_f32_16x16x32_bf16 v[114:117], v[144:147], v[176:179], v[114:117]
	v_mfma_f32_16x16x32_bf16 v[110:113], v[136:139], v[184:187], v[110:113]
	v_mfma_f32_16x16x32_bf16 v[106:109], v[144:147], v[184:187], v[106:109]
	v_mfma_f32_16x16x32_bf16 v[102:105], v[136:139], v[216:219], v[102:105]
	v_mfma_f32_16x16x32_bf16 v[98:101], v[144:147], v[216:219], v[98:101]
	v_mfma_f32_16x16x32_bf16 v[94:97], v[148:151], v[164:167], v[94:97]
	v_mfma_f32_16x16x32_bf16 v[90:93], v[156:159], v[164:167], v[90:93]
	v_mfma_f32_16x16x32_bf16 v[86:89], v[148:151], v[172:175], v[86:89]
	v_mfma_f32_16x16x32_bf16 v[82:85], v[156:159], v[172:175], v[82:85]
	v_mfma_f32_16x16x32_bf16 v[78:81], v[148:151], v[180:183], v[78:81]
	v_mfma_f32_16x16x32_bf16 v[74:77], v[156:159], v[180:183], v[74:77]
	v_mfma_f32_16x16x32_bf16 v[70:73], v[148:151], v[188:191], v[70:73]
	v_mfma_f32_16x16x32_bf16 v[66:69], v[156:159], v[188:191], v[66:69]
	v_mfma_f32_16x16x32_bf16 v[94:97], v[152:155], v[168:171], v[94:97]
	v_mfma_f32_16x16x32_bf16 v[90:93], v[160:163], v[168:171], v[90:93]
	v_mfma_f32_16x16x32_bf16 v[86:89], v[152:155], v[176:179], v[86:89]
	v_mfma_f32_16x16x32_bf16 v[82:85], v[160:163], v[176:179], v[82:85]
	v_mfma_f32_16x16x32_bf16 v[78:81], v[152:155], v[184:187], v[78:81]
	v_mfma_f32_16x16x32_bf16 v[74:77], v[160:163], v[184:187], v[74:77]
	v_mfma_f32_16x16x32_bf16 v[70:73], v[152:155], v[216:219], v[70:73]
	v_mfma_f32_16x16x32_bf16 v[66:69], v[160:163], v[216:219], v[66:69]
	s_setprio 0
	s_barrier
	s_mov_b32 m0, s67
	s_add_i32 s83, s82, 0x80
	ds_read_b128 v[164:167], v213 offset:49152
	ds_read_b128 v[168:171], v213 offset:50176
	ds_read_b128 v[172:175], v213 offset:51200
	ds_read_b128 v[176:179], v213 offset:52224
	ds_read_b128 v[180:183], v213 offset:53248
	ds_read_b128 v[184:187], v213 offset:54272
	ds_read_b128 v[188:191], v213 offset:55296
	ds_read_b128 v[216:219], v213 offset:56320
	buffer_load_dwordx4 v203, s[40:43], s83 offen lds
	s_mov_b32 m0, s68
	s_add_i32 s82, s82, 0x80080
	buffer_load_dwordx4 v205, s[40:43], s83 offen lds
	s_mov_b32 m0, s71
	s_addk_i32 s81, 0x80
	buffer_load_dwordx4 v203, s[40:43], s82 offen lds
	s_mov_b32 m0, s72
	s_nop 0
	buffer_load_dwordx4 v205, s[40:43], s82 offen lds
	s_mov_b32 m0, s69
	s_nop 0
	buffer_load_dwordx4 v202, s[60:63], s81 offen lds
	s_mov_b32 m0, s70
	s_nop 0
	buffer_load_dwordx4 v204, s[60:63], s81 offen lds
	s_waitcnt vmcnt(8)
	s_waitcnt lgkmcnt(0)
	s_setprio 1
	s_barrier
	v_mfma_f32_16x16x32_bf16 v[62:65], v[132:135], v[164:167], v[62:65]
	v_mfma_f32_16x16x32_bf16 v[58:61], v[140:143], v[164:167], v[58:61]
	v_mfma_f32_16x16x32_bf16 v[54:57], v[132:135], v[172:175], v[54:57]
	v_mfma_f32_16x16x32_bf16 v[50:53], v[140:143], v[172:175], v[50:53]
	v_mfma_f32_16x16x32_bf16 v[46:49], v[132:135], v[180:183], v[46:49]
	v_mfma_f32_16x16x32_bf16 v[42:45], v[140:143], v[180:183], v[42:45]
	v_mfma_f32_16x16x32_bf16 v[38:41], v[132:135], v[188:191], v[38:41]
	v_mfma_f32_16x16x32_bf16 v[34:37], v[140:143], v[188:191], v[34:37]
	v_mfma_f32_16x16x32_bf16 v[62:65], v[136:139], v[168:171], v[62:65]
	v_mfma_f32_16x16x32_bf16 v[58:61], v[144:147], v[168:171], v[58:61]
	v_mfma_f32_16x16x32_bf16 v[54:57], v[136:139], v[176:179], v[54:57]
	v_mfma_f32_16x16x32_bf16 v[50:53], v[144:147], v[176:179], v[50:53]
	v_mfma_f32_16x16x32_bf16 v[46:49], v[136:139], v[184:187], v[46:49]
	v_mfma_f32_16x16x32_bf16 v[42:45], v[144:147], v[184:187], v[42:45]
	v_mfma_f32_16x16x32_bf16 v[38:41], v[136:139], v[216:219], v[38:41]
	v_mfma_f32_16x16x32_bf16 v[34:37], v[144:147], v[216:219], v[34:37]
	v_mfma_f32_16x16x32_bf16 v[30:33], v[148:151], v[164:167], v[30:33]
	v_mfma_f32_16x16x32_bf16 v[26:29], v[156:159], v[164:167], v[26:29]
	v_mfma_f32_16x16x32_bf16 v[22:25], v[148:151], v[172:175], v[22:25]
	v_mfma_f32_16x16x32_bf16 v[18:21], v[156:159], v[172:175], v[18:21]
	v_mfma_f32_16x16x32_bf16 v[14:17], v[148:151], v[180:183], v[14:17]
	v_mfma_f32_16x16x32_bf16 v[10:13], v[156:159], v[180:183], v[10:13]
	v_mfma_f32_16x16x32_bf16 v[6:9], v[148:151], v[188:191], v[6:9]
	v_mfma_f32_16x16x32_bf16 v[2:5], v[156:159], v[188:191], v[2:5]
	v_mfma_f32_16x16x32_bf16 v[30:33], v[152:155], v[168:171], v[30:33]
	v_mfma_f32_16x16x32_bf16 v[26:29], v[160:163], v[168:171], v[26:29]
	v_mfma_f32_16x16x32_bf16 v[22:25], v[152:155], v[176:179], v[22:25]
	v_mfma_f32_16x16x32_bf16 v[18:21], v[160:163], v[176:179], v[18:21]
	v_mfma_f32_16x16x32_bf16 v[14:17], v[152:155], v[184:187], v[14:17]
	v_mfma_f32_16x16x32_bf16 v[10:13], v[160:163], v[184:187], v[10:13]
	v_mfma_f32_16x16x32_bf16 v[6:9], v[152:155], v[216:219], v[6:9]
	v_mfma_f32_16x16x32_bf16 v[2:5], v[160:163], v[216:219], v[2:5]
	s_setprio 0
	s_barrier
	s_add_i32 s80, s80, 2
	s_add_u32 s46, s46, 0x100
	s_addc_u32 s47, s47, 0
	s_cmp_gt_u32 s80, 29
	s_cbranch_scc0 .LBB0_789
	s_and_b64 vcc, exec, s[6:7]
	s_cbranch_vccz .LBB0_792
	s_barrier

; #define PG8_STAGEA(bufoff, goff, voff) PG8_STAGEX(rsA, bufoff, goff, voff)
; #define PG8_STAGEB(bufoff, goff, voff) PG8_STAGEX(rsB, bufoff, goff, voff)
; #define PG8_LDA(dst, b, h) do { _Pragma("unroll") for (int m = 0; m < 4; ++m) _Pragma("unroll") for (int k = 0; k < 2; ++k) dst[m][k] = *(const PG8_LAS bf16x8*)(lds + PG8_SA(b, h) + aoff + m * 2048 + k * 1024); } while (0)
; #define PG8_MMA(ai, bj, At, Bt) do { __builtin_amdgcn_s_setprio(1); _Pragma("unroll") for (int m = 0; m < 4; ++m) _Pragma("unroll") for (int n = 0; n < 2; ++n) _Pragma("unroll") for (int k = 0; k < 2; ++k) \
;         acc[ai][bj][m][n] = __builtin_amdgcn_mfma_f32_16x16x32_bf16(Bt[n][k], At[m][k], acc[ai][bj][m][n], 0, 0, 0); __builtin_amdgcn_s_setprio(0); } while (0)
; #define PG8_WAIT_V(n) asm volatile("s_waitcnt vmcnt(" #n ")" ::: "memory")
; #define PG8_WAIT_L(n) asm volatile("s_waitcnt lgkmcnt(" #n ")" ::: "memory")
; #define PG8_BAR __builtin_amdgcn_s_barrier()
; #define PG8_SCHED __builtin_amdgcn_sched_barrier(0)
; template <class Epi, class Sched, bool ALIGN_EPI = false, bool SP2 = false>
; __device__ __forceinline__ void gemm_phase(PG8_LAS unsigned char* lds, const Gemm g, const Sched& S, const Epi& E) {
;     ...
;             PG8_WAIT_V(8); PG8_WAIT_L(0); PG8_BAR; PG8_MMA(0, 0, At, B0); PG8_MMA(0, 1, At, B1); PG8_BAR; PG8_SCHED;
;             PG8_LDA(At, 0, 1); PG8_STAGEB(PG8_SB(0, 0), b2, voffB); PG8_STAGEB(PG8_SB(0, 1), b2 + hstep, voffB); PG8_STAGEA(PG8_SA(0, 0), a2, voffA);
;             PG8_WAIT_V(8); PG8_WAIT_L(0); PG8_BAR; PG8_MMA(1, 0, At, B0); PG8_MMA(1, 1, At, B1); PG8_BAR; PG8_SCHED;
.LBB0_940:
	s_waitcnt vmcnt(8)
	s_waitcnt lgkmcnt(0)
	s_setprio 1
	s_barrier
	v_mfma_f32_16x16x32_bf16 v[126:129], v[146:149], v[186:189], v[126:129]
	v_mfma_f32_16x16x32_bf16 v[122:125], v[154:157], v[186:189], v[122:125]
	v_mfma_f32_16x16x32_bf16 v[114:117], v[146:149], v[178:181], v[114:117]
	v_mfma_f32_16x16x32_bf16 v[106:109], v[154:157], v[178:181], v[106:109]
	v_mfma_f32_16x16x32_bf16 v[98:101], v[146:149], v[170:173], v[98:101]
	v_mfma_f32_16x16x32_bf16 v[90:93], v[154:157], v[170:173], v[90:93]
	v_mfma_f32_16x16x32_bf16 v[82:85], v[146:149], v[162:165], v[82:85]
	v_mfma_f32_16x16x32_bf16 v[74:77], v[154:157], v[162:165], v[74:77]
	v_mfma_f32_16x16x32_bf16 v[126:129], v[150:153], v[190:193], v[126:129]
	v_mfma_f32_16x16x32_bf16 v[122:125], v[158:161], v[190:193], v[122:125]
	v_mfma_f32_16x16x32_bf16 v[114:117], v[150:153], v[182:185], v[114:117]
	v_mfma_f32_16x16x32_bf16 v[106:109], v[158:161], v[182:185], v[106:109]
	v_mfma_f32_16x16x32_bf16 v[98:101], v[150:153], v[174:177], v[98:101]
	v_mfma_f32_16x16x32_bf16 v[90:93], v[158:161], v[174:177], v[90:93]
	v_mfma_f32_16x16x32_bf16 v[82:85], v[150:153], v[166:169], v[82:85]
	v_mfma_f32_16x16x32_bf16 v[74:77], v[158:161], v[166:169], v[74:77]
	v_mfma_f32_16x16x32_bf16 v[118:121], v[130:133], v[186:189], v[118:121]
	v_mfma_f32_16x16x32_bf16 v[110:113], v[138:141], v[186:189], v[110:113]
	v_mfma_f32_16x16x32_bf16 v[102:105], v[130:133], v[178:181], v[102:105]
	v_mfma_f32_16x16x32_bf16 v[94:97], v[138:141], v[178:181], v[94:97]
	v_mfma_f32_16x16x32_bf16 v[86:89], v[130:133], v[170:173], v[86:89]
	v_mfma_f32_16x16x32_bf16 v[78:81], v[138:141], v[170:173], v[78:81]
	v_mfma_f32_16x16x32_bf16 v[70:73], v[130:133], v[162:165], v[70:73]
	v_mfma_f32_16x16x32_bf16 v[66:69], v[138:141], v[162:165], v[66:69]
	v_mfma_f32_16x16x32_bf16 v[118:121], v[134:137], v[190:193], v[118:121]
	v_mfma_f32_16x16x32_bf16 v[110:113], v[142:145], v[190:193], v[110:113]
	v_mfma_f32_16x16x32_bf16 v[102:105], v[134:137], v[182:185], v[102:105]
	v_mfma_f32_16x16x32_bf16 v[94:97], v[142:145], v[182:185], v[94:97]
	v_mfma_f32_16x16x32_bf16 v[86:89], v[134:137], v[174:177], v[86:89]
	v_mfma_f32_16x16x32_bf16 v[78:81], v[142:145], v[174:177], v[78:81]
	v_mfma_f32_16x16x32_bf16 v[70:73], v[134:137], v[166:169], v[70:73]
	v_mfma_f32_16x16x32_bf16 v[66:69], v[142:145], v[166:169], v[66:69]
	s_setprio 0
	s_barrier
	s_mov_b32 m0, s40
	s_add_i32 s23, s18, 0x100
	s_mov_b32 s14, s30
	s_mov_b32 s15, s31
	ds_read_b128 v[162:165], v204 offset:16384
	ds_read_b128 v[166:169], v204 offset:17408
	ds_read_b128 v[170:173], v204 offset:18432
	ds_read_b128 v[174:177], v204 offset:19456
	ds_read_b128 v[178:181], v204 offset:20480
	ds_read_b128 v[182:185], v204 offset:21504
	ds_read_b128 v[186:189], v204 offset:22528
	ds_read_b128 v[190:193], v204 offset:23552
	buffer_load_dwordx4 v200, s[12:15], s23 offen lds
	s_mov_b32 m0, s41
	s_nop 0
	buffer_load_dwordx4 v201, s[12:15], s23 offen lds
	s_add_i32 s23, s18, 0x160100
	s_mov_b32 m0, s42
	s_nop 0
	buffer_load_dwordx4 v200, s[12:15], s23 offen lds
	s_mov_b32 m0, s43
	s_nop 0
	buffer_load_dwordx4 v201, s[12:15], s23 offen lds
	s_add_i32 s23, s20, 0x100
	s_mov_b32 m0, s39
	s_nop 0
	buffer_load_dwordx4 v200, s[28:31], s23 offen lds
	s_mov_b32 m0, s44
	s_nop 0
	buffer_load_dwordx4 v201, s[28:31], s23 offen lds
	s_waitcnt vmcnt(8)
	s_waitcnt lgkmcnt(0)
	s_setprio 1
	s_barrier
	v_mfma_f32_16x16x32_bf16 v[62:65], v[146:149], v[162:165], v[62:65]
	v_mfma_f32_16x16x32_bf16 v[58:61], v[154:157], v[162:165], v[58:61]
	v_mfma_f32_16x16x32_bf16 v[50:53], v[146:149], v[170:173], v[50:53]
	v_mfma_f32_16x16x32_bf16 v[42:45], v[154:157], v[170:173], v[42:45]
	v_mfma_f32_16x16x32_bf16 v[34:37], v[146:149], v[178:181], v[34:37]
	v_mfma_f32_16x16x32_bf16 v[26:29], v[154:157], v[178:181], v[26:29]
	v_mfma_f32_16x16x32_bf16 v[18:21], v[146:149], v[186:189], v[18:21]
	v_mfma_f32_16x16x32_bf16 v[10:13], v[154:157], v[186:189], v[10:13]
	v_mfma_f32_16x16x32_bf16 v[62:65], v[150:153], v[166:169], v[62:65]
	v_mfma_f32_16x16x32_bf16 v[58:61], v[158:161], v[166:169], v[58:61]
	v_mfma_f32_16x16x32_bf16 v[50:53], v[150:153], v[174:177], v[50:53]
	v_mfma_f32_16x16x32_bf16 v[42:45], v[158:161], v[174:177], v[42:45]
	v_mfma_f32_16x16x32_bf16 v[34:37], v[150:153], v[182:185], v[34:37]
	v_mfma_f32_16x16x32_bf16 v[26:29], v[158:161], v[182:185], v[26:29]
	v_mfma_f32_16x16x32_bf16 v[18:21], v[150:153], v[190:193], v[18:21]
	v_mfma_f32_16x16x32_bf16 v[10:13], v[158:161], v[190:193], v[10:13]
	v_mfma_f32_16x16x32_bf16 v[54:57], v[130:133], v[162:165], v[54:57]
	v_mfma_f32_16x16x32_bf16 v[46:49], v[138:141], v[162:165], v[46:49]
	v_mfma_f32_16x16x32_bf16 v[38:41], v[130:133], v[170:173], v[38:41]
	v_mfma_f32_16x16x32_bf16 v[30:33], v[138:141], v[170:173], v[30:33]
	v_mfma_f32_16x16x32_bf16 v[22:25], v[130:133], v[178:181], v[22:25]
	v_mfma_f32_16x16x32_bf16 v[14:17], v[138:141], v[178:181], v[14:17]
	v_mfma_f32_16x16x32_bf16 v[6:9], v[130:133], v[186:189], v[6:9]
	v_mfma_f32_16x16x32_bf16 v[2:5], v[138:141], v[186:189], v[2:5]
	v_mfma_f32_16x16x32_bf16 v[54:57], v[134:137], v[166:169], v[54:57]
	v_mfma_f32_16x16x32_bf16 v[46:49], v[142:145], v[166:169], v[46:49]
	v_mfma_f32_16x16x32_bf16 v[38:41], v[134:137], v[174:177], v[38:41]
	v_mfma_f32_16x16x32_bf16 v[30:33], v[142:145], v[174:177], v[30:33]
	v_mfma_f32_16x16x32_bf16 v[22:25], v[134:137], v[182:185], v[22:25]
	v_mfma_f32_16x16x32_bf16 v[14:17], v[142:145], v[182:185], v[14:17]
	v_mfma_f32_16x16x32_bf16 v[6:9], v[134:137], v[190:193], v[6:9]
	v_mfma_f32_16x16x32_bf16 v[2:5], v[142:145], v[190:193], v[2:5]
	s_setprio 0
	s_barrier
; #define PG8_STAGEA(bufoff, goff, voff) PG8_STAGEX(rsA, bufoff, goff, voff)
; #define PG8_STAGEB(bufoff, goff, voff) PG8_STAGEX(rsB, bufoff, goff, voff)
; #define PG8_LDA(dst, b, h) do { _Pragma("unroll") for (int m = 0; m < 4; ++m) _Pragma("unroll") for (int k = 0; k < 2; ++k) dst[m][k] = *(const PG8_LAS bf16x8*)(lds + PG8_SA(b, h) + aoff + m * 2048 + k * 1024); } while (0)
; #define PG8_LDB(dst, b, h) do { _Pragma("unroll") for (int n = 0; n < 2; ++n) _Pragma("unroll") for (int k = 0; k < 2; ++k) dst[n][k] = *(const PG8_LAS bf16x8*)(lds + PG8_SB(b, h) + boff + n * 2048 + k * 1024); } while (0)
; #define PG8_MMA(ai, bj, At, Bt) do { __builtin_amdgcn_s_setprio(1); _Pragma("unroll") for (int m = 0; m < 4; ++m) _Pragma("unroll") for (int n = 0; n < 2; ++n) _Pragma("unroll") for (int k = 0; k < 2; ++k) \
;         acc[ai][bj][m][n] = __builtin_amdgcn_mfma_f32_16x16x32_bf16(Bt[n][k], At[m][k], acc[ai][bj][m][n], 0, 0, 0); __builtin_amdgcn_s_setprio(0); } while (0)
; #define PG8_WAIT_V(n) asm volatile("s_waitcnt vmcnt(" #n ")" ::: "memory")
; #define PG8_WAIT_L(n) asm volatile("s_waitcnt lgkmcnt(" #n ")" ::: "memory")
; #define PG8_BAR __builtin_amdgcn_s_barrier()
; #define PG8_SCHED __builtin_amdgcn_sched_barrier(0)
; template <class Epi, class Sched, bool ALIGN_EPI = false, bool SP2 = false>
; __device__ __forceinline__ void gemm_phase(PG8_LAS unsigned char* lds, const Gemm g, const Sched& S, const Epi& E) {
;     ...
;             PG8_LDB(B0, 1, 0); PG8_LDB(B1, 1, 1); PG8_SCHED; PG8_LDA(At, 1, 0); PG8_STAGEA(PG8_SA(0, 1), a2 + hstep, voffA);
;             PG8_WAIT_V(8); PG8_WAIT_L(0); PG8_BAR; PG8_MMA(0, 0, At, B0); PG8_MMA(0, 1, At, B1); PG8_BAR; PG8_SCHED;
;             PG8_LDA(At, 1, 1); PG8_STAGEB(PG8_SB(1, 0), b3, voffB); PG8_STAGEB(PG8_SB(1, 1), b3 + hstep, voffB); PG8_STAGEA(PG8_SA(1, 0), a3, voffA);
;             PG8_WAIT_V(8); PG8_WAIT_L(0); PG8_BAR; PG8_MMA(1, 0, At, B0); PG8_MMA(1, 1, At, B1); PG8_BAR; PG8_SCHED;
	v_add_u32_e32 v130, 0x18000, v203
	v_add_u32_e32 v131, 0x1c000, v203
	ds_read_b128 v[132:135], v130
	ds_read_b128 v[136:139], v130 offset:1024
	ds_read_b128 v[140:143], v130 offset:2048
	ds_read_b128 v[144:147], v130 offset:3072
	ds_read_b128 v[148:151], v131
	ds_read_b128 v[152:155], v131 offset:1024
	ds_read_b128 v[156:159], v131 offset:2048
	ds_read_b128 v[160:163], v131 offset:3072
	s_add_i32 s23, s20, 0x160100
	s_mov_b32 m0, s45
	ds_read_b128 v[164:167], v204 offset:32768
	ds_read_b128 v[168:171], v204 offset:33792
	ds_read_b128 v[172:175], v204 offset:34816
	ds_read_b128 v[176:179], v204 offset:35840
	ds_read_b128 v[180:183], v204 offset:36864
	ds_read_b128 v[184:187], v204 offset:37888
	ds_read_b128 v[188:191], v204 offset:38912
	ds_read_b128 v[208:211], v204 offset:39936
	buffer_load_dwordx4 v200, s[28:31], s23 offen lds
	s_mov_b32 m0, s47
	s_nop 0
	buffer_load_dwordx4 v201, s[28:31], s23 offen lds
	s_waitcnt vmcnt(8)
	s_waitcnt lgkmcnt(0)
	s_setprio 1
	s_barrier
	v_mfma_f32_16x16x32_bf16 v[126:129], v[132:135], v[164:167], v[126:129]
	v_mfma_f32_16x16x32_bf16 v[122:125], v[140:143], v[164:167], v[122:125]
	v_mfma_f32_16x16x32_bf16 v[114:117], v[132:135], v[172:175], v[114:117]
	v_mfma_f32_16x16x32_bf16 v[106:109], v[140:143], v[172:175], v[106:109]
	v_mfma_f32_16x16x32_bf16 v[98:101], v[132:135], v[180:183], v[98:101]
	v_mfma_f32_16x16x32_bf16 v[90:93], v[140:143], v[180:183], v[90:93]
	v_mfma_f32_16x16x32_bf16 v[82:85], v[132:135], v[188:191], v[82:85]
	v_mfma_f32_16x16x32_bf16 v[74:77], v[140:143], v[188:191], v[74:77]
	v_mfma_f32_16x16x32_bf16 v[126:129], v[136:139], v[168:171], v[126:129]
	v_mfma_f32_16x16x32_bf16 v[122:125], v[144:147], v[168:171], v[122:125]
	v_mfma_f32_16x16x32_bf16 v[114:117], v[136:139], v[176:179], v[114:117]
	v_mfma_f32_16x16x32_bf16 v[106:109], v[144:147], v[176:179], v[106:109]
	v_mfma_f32_16x16x32_bf16 v[98:101], v[136:139], v[184:187], v[98:101]
	v_mfma_f32_16x16x32_bf16 v[90:93], v[144:147], v[184:187], v[90:93]
	v_mfma_f32_16x16x32_bf16 v[82:85], v[136:139], v[208:211], v[82:85]
	v_mfma_f32_16x16x32_bf16 v[74:77], v[144:147], v[208:211], v[74:77]
	v_mfma_f32_16x16x32_bf16 v[118:121], v[148:151], v[164:167], v[118:121]
	v_mfma_f32_16x16x32_bf16 v[110:113], v[156:159], v[164:167], v[110:113]
	v_mfma_f32_16x16x32_bf16 v[102:105], v[148:151], v[172:175], v[102:105]
	v_mfma_f32_16x16x32_bf16 v[94:97], v[156:159], v[172:175], v[94:97]
	v_mfma_f32_16x16x32_bf16 v[86:89], v[148:151], v[180:183], v[86:89]
	v_mfma_f32_16x16x32_bf16 v[78:81], v[156:159], v[180:183], v[78:81]
	v_mfma_f32_16x16x32_bf16 v[70:73], v[148:151], v[188:191], v[70:73]
	v_mfma_f32_16x16x32_bf16 v[66:69], v[156:159], v[188:191], v[66:69]
	v_mfma_f32_16x16x32_bf16 v[118:121], v[152:155], v[168:171], v[118:121]
	v_mfma_f32_16x16x32_bf16 v[110:113], v[160:163], v[168:171], v[110:113]
	v_mfma_f32_16x16x32_bf16 v[102:105], v[152:155], v[176:179], v[102:105]
	v_mfma_f32_16x16x32_bf16 v[94:97], v[160:163], v[176:179], v[94:97]
	v_mfma_f32_16x16x32_bf16 v[86:89], v[152:155], v[184:187], v[86:89]
	v_mfma_f32_16x16x32_bf16 v[78:81], v[160:163], v[184:187], v[78:81]
	v_mfma_f32_16x16x32_bf16 v[70:73], v[152:155], v[208:211], v[70:73]
	v_mfma_f32_16x16x32_bf16 v[66:69], v[160:163], v[208:211], v[66:69]
	s_setprio 0
	s_barrier
	s_mov_b32 m0, s49
	s_add_i32 s23, s18, 0x180
	ds_read_b128 v[164:167], v204 offset:49152
	ds_read_b128 v[168:171], v204 offset:50176
	ds_read_b128 v[172:175], v204 offset:51200
	ds_read_b128 v[176:179], v204 offset:52224
	ds_read_b128 v[180:183], v204 offset:53248
	ds_read_b128 v[184:187], v204 offset:54272
	ds_read_b128 v[188:191], v204 offset:55296
	ds_read_b128 v[208:211], v204 offset:56320
	buffer_load_dwordx4 v200, s[12:15], s23 offen lds
	s_mov_b32 m0, s50
	s_nop 0
	buffer_load_dwordx4 v201, s[12:15], s23 offen lds
	s_add_i32 s23, s18, 0x160180
	s_mov_b32 m0, s57
	s_nop 0
	buffer_load_dwordx4 v200, s[12:15], s23 offen lds
	s_mov_b32 m0, s58
	s_nop 0
	buffer_load_dwordx4 v201, s[12:15], s23 offen lds
	s_add_i32 s23, s20, 0x180
	s_mov_b32 m0, s51
	s_nop 0
	buffer_load_dwordx4 v200, s[28:31], s23 offen lds
	s_mov_b32 m0, s56
	s_nop 0
	buffer_load_dwordx4 v201, s[28:31], s23 offen lds
	s_waitcnt vmcnt(8)
	s_waitcnt lgkmcnt(0)
	s_setprio 1
	s_barrier
	v_mfma_f32_16x16x32_bf16 v[62:65], v[132:135], v[164:167], v[62:65]
	v_mfma_f32_16x16x32_bf16 v[58:61], v[140:143], v[164:167], v[58:61]
	v_mfma_f32_16x16x32_bf16 v[50:53], v[132:135], v[172:175], v[50:53]
	v_mfma_f32_16x16x32_bf16 v[42:45], v[140:143], v[172:175], v[42:45]
	v_mfma_f32_16x16x32_bf16 v[34:37], v[132:135], v[180:183], v[34:37]
	v_mfma_f32_16x16x32_bf16 v[26:29], v[140:143], v[180:183], v[26:29]
	v_mfma_f32_16x16x32_bf16 v[18:21], v[132:135], v[188:191], v[18:21]
	v_mfma_f32_16x16x32_bf16 v[10:13], v[140:143], v[188:191], v[10:13]
	v_mfma_f32_16x16x32_bf16 v[62:65], v[136:139], v[168:171], v[62:65]
	v_mfma_f32_16x16x32_bf16 v[58:61], v[144:147], v[168:171], v[58:61]
	v_mfma_f32_16x16x32_bf16 v[50:53], v[136:139], v[176:179], v[50:53]
	v_mfma_f32_16x16x32_bf16 v[42:45], v[144:147], v[176:179], v[42:45]
	v_mfma_f32_16x16x32_bf16 v[34:37], v[136:139], v[184:187], v[34:37]
	v_mfma_f32_16x16x32_bf16 v[26:29], v[144:147], v[184:187], v[26:29]
	v_mfma_f32_16x16x32_bf16 v[18:21], v[136:139], v[208:211], v[18:21]
	v_mfma_f32_16x16x32_bf16 v[10:13], v[144:147], v[208:211], v[10:13]
	v_mfma_f32_16x16x32_bf16 v[54:57], v[148:151], v[164:167], v[54:57]
	v_mfma_f32_16x16x32_bf16 v[46:49], v[156:159], v[164:167], v[46:49]
	v_mfma_f32_16x16x32_bf16 v[38:41], v[148:151], v[172:175], v[38:41]
	v_mfma_f32_16x16x32_bf16 v[30:33], v[156:159], v[172:175], v[30:33]
	v_mfma_f32_16x16x32_bf16 v[22:25], v[148:151], v[180:183], v[22:25]
	v_mfma_f32_16x16x32_bf16 v[14:17], v[156:159], v[180:183], v[14:17]
	v_mfma_f32_16x16x32_bf16 v[6:9], v[148:151], v[188:191], v[6:9]
	v_mfma_f32_16x16x32_bf16 v[2:5], v[156:159], v[188:191], v[2:5]
	v_mfma_f32_16x16x32_bf16 v[54:57], v[152:155], v[168:171], v[54:57]
	v_mfma_f32_16x16x32_bf16 v[46:49], v[160:163], v[168:171], v[46:49]
	v_mfma_f32_16x16x32_bf16 v[38:41], v[152:155], v[176:179], v[38:41]
	v_mfma_f32_16x16x32_bf16 v[30:33], v[160:163], v[176:179], v[30:33]
	v_mfma_f32_16x16x32_bf16 v[22:25], v[152:155], v[184:187], v[22:25]
	v_mfma_f32_16x16x32_bf16 v[14:17], v[160:163], v[184:187], v[14:17]
	v_mfma_f32_16x16x32_bf16 v[6:9], v[152:155], v[208:211], v[6:9]
	v_mfma_f32_16x16x32_bf16 v[2:5], v[160:163], v[208:211], v[2:5]
	s_setprio 0
	s_barrier
	s_mov_b32 s23, 0
	s_mov_b64 s[34:35], 0x160180
; #define PG8_STAGEA(bufoff, goff, voff) PG8_STAGEX(rsA, bufoff, goff, voff)
; #define PG8_STAGEB(bufoff, goff, voff) PG8_STAGEX(rsB, bufoff, goff, voff)
; #define PG8_LDA(dst, b, h) do { _Pragma("unroll") for (int m = 0; m < 4; ++m) _Pragma("unroll") for (int k = 0; k < 2; ++k) dst[m][k] = *(const PG8_LAS bf16x8*)(lds + PG8_SA(b, h) + aoff + m * 2048 + k * 1024); } while (0)
; #define PG8_LDB(dst, b, h) do { _Pragma("unroll") for (int n = 0; n < 2; ++n) _Pragma("unroll") for (int k = 0; k < 2; ++k) dst[n][k] = *(const PG8_LAS bf16x8*)(lds + PG8_SB(b, h) + boff + n * 2048 + k * 1024); } while (0)
; #define PG8_MMA(ai, bj, At, Bt) do { __builtin_amdgcn_s_setprio(1); _Pragma("unroll") for (int m = 0; m < 4; ++m) _Pragma("unroll") for (int n = 0; n < 2; ++n) _Pragma("unroll") for (int k = 0; k < 2; ++k) \
;         acc[ai][bj][m][n] = __builtin_amdgcn_mfma_f32_16x16x32_bf16(Bt[n][k], At[m][k], acc[ai][bj][m][n], 0, 0, 0); __builtin_amdgcn_s_setprio(0); } while (0)
; #define PG8_WAIT_V(n) asm volatile("s_waitcnt vmcnt(" #n ")" ::: "memory")
; #define PG8_WAIT_L(n) asm volatile("s_waitcnt lgkmcnt(" #n ")" ::: "memory")
; #define PG8_BAR __builtin_amdgcn_s_barrier()
; #define PG8_SCHED __builtin_amdgcn_sched_barrier(0)
; template <class Epi, class Sched, bool ALIGN_EPI = false, bool SP2 = false>
; __device__ __forceinline__ void gemm_phase(PG8_LAS unsigned char* lds, const Gemm g, const Sched& S, const Epi& E) {
;     ...
;             PG8_LDB(B0, 0, 0); PG8_LDB(B1, 0, 1); PG8_SCHED; PG8_LDA(At, 0, 0); PG8_STAGEA(PG8_SA(1, 1), a1 + hstep, voffA);
;             if (t == 0 && ui > 0) {
; #pragma unroll
;                 for (int a = 0; a < 2; ++a)
; #pragma unroll
;                     for (int b = 0; b < 2; ++b)
; #pragma unroll
;                         for (int m = 0; m < 4; ++m)
; #pragma unroll
;                             for (int n = 0; n < 2; ++n) acc[a][b][m][n] = (f32x4){0.f, 0.f, 0.f, 0.f}; }
;             PG8_WAIT_V(8); PG8_WAIT_L(0); PG8_BAR; PG8_MMA(0, 0, At, B0); PG8_MMA(0, 1, At, B1); PG8_BAR; PG8_SCHED;
;             PG8_LDA(At, 0, 1); PG8_STAGEB(PG8_SB(0, 0), b2, voffB); PG8_STAGEB(PG8_SB(0, 1), b2 + hstep, voffB); PG8_STAGEA(PG8_SA(0, 0), a2, voffA);
;             PG8_WAIT_V(8); PG8_WAIT_L(0); PG8_BAR; PG8_MMA(1, 0, At, B0); PG8_MMA(1, 1, At, B1); PG8_BAR; PG8_SCHED;
.LBB0_941:
	ds_read_b128 v[132:135], v205
	ds_read_b128 v[136:139], v205 offset:1024
	ds_read_b128 v[140:143], v205 offset:2048
	ds_read_b128 v[144:147], v205 offset:3072
	ds_read_b128 v[148:151], v206
	ds_read_b128 v[152:155], v206 offset:1024
	ds_read_b128 v[156:159], v206 offset:2048
	ds_read_b128 v[160:163], v206 offset:3072
	s_mov_b32 m0, s59
	s_add_i32 s63, s20, s34
	ds_read_b128 v[164:167], v204
	ds_read_b128 v[168:171], v204 offset:1024
	ds_read_b128 v[172:175], v204 offset:2048
	ds_read_b128 v[176:179], v204 offset:3072
	ds_read_b128 v[180:183], v204 offset:4096
	ds_read_b128 v[184:187], v204 offset:5120
	ds_read_b128 v[188:191], v204 offset:6144
	ds_read_b128 v[208:211], v204 offset:7168
	buffer_load_dwordx4 v200, s[28:31], s63 offen lds
	s_mov_b32 m0, s60
	s_add_i32 s64, s18, s34
	buffer_load_dwordx4 v201, s[28:31], s63 offen lds
	s_waitcnt vmcnt(8)
	s_waitcnt lgkmcnt(0)
	s_add_i32 s64, s64, 0xffea0080
	s_add_i32 s63, s63, 0xffea0080
	s_cmpk_eq_i32 s23, 0x54
	s_setprio 1
	s_barrier
	v_mfma_f32_16x16x32_bf16 v[126:129], v[132:135], v[164:167], v[126:129]
	v_mfma_f32_16x16x32_bf16 v[122:125], v[140:143], v[164:167], v[122:125]
	v_mfma_f32_16x16x32_bf16 v[114:117], v[132:135], v[172:175], v[114:117]
	v_mfma_f32_16x16x32_bf16 v[106:109], v[140:143], v[172:175], v[106:109]
	v_mfma_f32_16x16x32_bf16 v[98:101], v[132:135], v[180:183], v[98:101]
	v_mfma_f32_16x16x32_bf16 v[90:93], v[140:143], v[180:183], v[90:93]
	v_mfma_f32_16x16x32_bf16 v[82:85], v[132:135], v[188:191], v[82:85]
	v_mfma_f32_16x16x32_bf16 v[74:77], v[140:143], v[188:191], v[74:77]
	v_mfma_f32_16x16x32_bf16 v[126:129], v[136:139], v[168:171], v[126:129]
	v_mfma_f32_16x16x32_bf16 v[122:125], v[144:147], v[168:171], v[122:125]
	v_mfma_f32_16x16x32_bf16 v[114:117], v[136:139], v[176:179], v[114:117]
	v_mfma_f32_16x16x32_bf16 v[106:109], v[144:147], v[176:179], v[106:109]
	v_mfma_f32_16x16x32_bf16 v[98:101], v[136:139], v[184:187], v[98:101]
	v_mfma_f32_16x16x32_bf16 v[90:93], v[144:147], v[184:187], v[90:93]
	v_mfma_f32_16x16x32_bf16 v[82:85], v[136:139], v[208:211], v[82:85]
	v_mfma_f32_16x16x32_bf16 v[74:77], v[144:147], v[208:211], v[74:77]
	v_mfma_f32_16x16x32_bf16 v[118:121], v[148:151], v[164:167], v[118:121]
	v_mfma_f32_16x16x32_bf16 v[110:113], v[156:159], v[164:167], v[110:113]
	v_mfma_f32_16x16x32_bf16 v[102:105], v[148:151], v[172:175], v[102:105]
	v_mfma_f32_16x16x32_bf16 v[94:97], v[156:159], v[172:175], v[94:97]
	v_mfma_f32_16x16x32_bf16 v[86:89], v[148:151], v[180:183], v[86:89]
	v_mfma_f32_16x16x32_bf16 v[78:81], v[156:159], v[180:183], v[78:81]
	v_mfma_f32_16x16x32_bf16 v[70:73], v[148:151], v[188:191], v[70:73]
	v_mfma_f32_16x16x32_bf16 v[66:69], v[156:159], v[188:191], v[66:69]
	v_mfma_f32_16x16x32_bf16 v[118:121], v[152:155], v[168:171], v[118:121]
	v_mfma_f32_16x16x32_bf16 v[110:113], v[160:163], v[168:171], v[110:113]
	v_mfma_f32_16x16x32_bf16 v[102:105], v[152:155], v[176:179], v[102:105]
	v_mfma_f32_16x16x32_bf16 v[94:97], v[160:163], v[176:179], v[94:97]
	v_mfma_f32_16x16x32_bf16 v[86:89], v[152:155], v[184:187], v[86:89]
	v_mfma_f32_16x16x32_bf16 v[78:81], v[160:163], v[184:187], v[78:81]
	v_mfma_f32_16x16x32_bf16 v[70:73], v[152:155], v[208:211], v[70:73]
	v_mfma_f32_16x16x32_bf16 v[66:69], v[160:163], v[208:211], v[66:69]
	s_setprio 0
	s_barrier
	s_mov_b32 m0, s40
	s_cselect_b32 s64, s4, s64
	ds_read_b128 v[164:167], v204 offset:16384
	ds_read_b128 v[168:171], v204 offset:17408
	ds_read_b128 v[172:175], v204 offset:18432
	ds_read_b128 v[176:179], v204 offset:19456
	ds_read_b128 v[180:183], v204 offset:20480
	ds_read_b128 v[184:187], v204 offset:21504
	ds_read_b128 v[188:191], v204 offset:22528
	ds_read_b128 v[208:211], v204 offset:23552
	buffer_load_dwordx4 v200, s[12:15], s64 offen lds
	s_mov_b32 m0, s41
	s_cselect_b32 s63, s24, s63
	buffer_load_dwordx4 v201, s[12:15], s64 offen lds
	s_add_i32 s65, s64, 0x160000
	s_mov_b32 m0, s42
	s_nop 0
	buffer_load_dwordx4 v200, s[12:15], s65 offen lds
	s_mov_b32 m0, s43
	s_nop 0
	buffer_load_dwordx4 v201, s[12:15], s65 offen lds
	s_mov_b32 m0, s39
	s_nop 0
	buffer_load_dwordx4 v200, s[28:31], s63 offen lds
	s_mov_b32 m0, s44
	s_nop 0
	buffer_load_dwordx4 v201, s[28:31], s63 offen lds
	s_waitcnt vmcnt(8)
	s_waitcnt lgkmcnt(0)
	s_setprio 1
	s_barrier
	v_mfma_f32_16x16x32_bf16 v[62:65], v[132:135], v[164:167], v[62:65]
	v_mfma_f32_16x16x32_bf16 v[58:61], v[140:143], v[164:167], v[58:61]
	v_mfma_f32_16x16x32_bf16 v[50:53], v[132:135], v[172:175], v[50:53]
	v_mfma_f32_16x16x32_bf16 v[42:45], v[140:143], v[172:175], v[42:45]
	v_mfma_f32_16x16x32_bf16 v[34:37], v[132:135], v[180:183], v[34:37]
	v_mfma_f32_16x16x32_bf16 v[26:29], v[140:143], v[180:183], v[26:29]
	v_mfma_f32_16x16x32_bf16 v[18:21], v[132:135], v[188:191], v[18:21]
	v_mfma_f32_16x16x32_bf16 v[10:13], v[140:143], v[188:191], v[10:13]
	v_mfma_f32_16x16x32_bf16 v[62:65], v[136:139], v[168:171], v[62:65]
	v_mfma_f32_16x16x32_bf16 v[58:61], v[144:147], v[168:171], v[58:61]
	v_mfma_f32_16x16x32_bf16 v[50:53], v[136:139], v[176:179], v[50:53]
	v_mfma_f32_16x16x32_bf16 v[42:45], v[144:147], v[176:179], v[42:45]
	v_mfma_f32_16x16x32_bf16 v[34:37], v[136:139], v[184:187], v[34:37]
	v_mfma_f32_16x16x32_bf16 v[26:29], v[144:147], v[184:187], v[26:29]
	v_mfma_f32_16x16x32_bf16 v[18:21], v[136:139], v[208:211], v[18:21]
	v_mfma_f32_16x16x32_bf16 v[10:13], v[144:147], v[208:211], v[10:13]
	v_mfma_f32_16x16x32_bf16 v[54:57], v[148:151], v[164:167], v[54:57]
	v_mfma_f32_16x16x32_bf16 v[46:49], v[156:159], v[164:167], v[46:49]
	v_mfma_f32_16x16x32_bf16 v[38:41], v[148:151], v[172:175], v[38:41]
	v_mfma_f32_16x16x32_bf16 v[30:33], v[156:159], v[172:175], v[30:33]
	v_mfma_f32_16x16x32_bf16 v[22:25], v[148:151], v[180:183], v[22:25]
	v_mfma_f32_16x16x32_bf16 v[14:17], v[156:159], v[180:183], v[14:17]
	v_mfma_f32_16x16x32_bf16 v[6:9], v[148:151], v[188:191], v[6:9]
	v_mfma_f32_16x16x32_bf16 v[2:5], v[156:159], v[188:191], v[2:5]
	v_mfma_f32_16x16x32_bf16 v[54:57], v[152:155], v[168:171], v[54:57]
	v_mfma_f32_16x16x32_bf16 v[46:49], v[160:163], v[168:171], v[46:49]
	v_mfma_f32_16x16x32_bf16 v[38:41], v[152:155], v[176:179], v[38:41]
	v_mfma_f32_16x16x32_bf16 v[30:33], v[160:163], v[176:179], v[30:33]
	v_mfma_f32_16x16x32_bf16 v[22:25], v[152:155], v[184:187], v[22:25]
	v_mfma_f32_16x16x32_bf16 v[14:17], v[160:163], v[184:187], v[14:17]
	v_mfma_f32_16x16x32_bf16 v[6:9], v[152:155], v[208:211], v[6:9]
	v_mfma_f32_16x16x32_bf16 v[2:5], v[160:163], v[208:211], v[2:5]
	s_setprio 0
	s_barrier
; #define PG8_STAGEA(bufoff, goff, voff) PG8_STAGEX(rsA, bufoff, goff, voff)
; #define PG8_STAGEB(bufoff, goff, voff) PG8_STAGEX(rsB, bufoff, goff, voff)
; #define PG8_LDA(dst, b, h) do { _Pragma("unroll") for (int m = 0; m < 4; ++m) _Pragma("unroll") for (int k = 0; k < 2; ++k) dst[m][k] = *(const PG8_LAS bf16x8*)(lds + PG8_SA(b, h) + aoff + m * 2048 + k * 1024); } while (0)
; #define PG8_LDB(dst, b, h) do { _Pragma("unroll") for (int n = 0; n < 2; ++n) _Pragma("unroll") for (int k = 0; k < 2; ++k) dst[n][k] = *(const PG8_LAS bf16x8*)(lds + PG8_SB(b, h) + boff + n * 2048 + k * 1024); } while (0)
; #define PG8_MMA(ai, bj, At, Bt) do { __builtin_amdgcn_s_setprio(1); _Pragma("unroll") for (int m = 0; m < 4; ++m) _Pragma("unroll") for (int n = 0; n < 2; ++n) _Pragma("unroll") for (int k = 0; k < 2; ++k) \
;         acc[ai][bj][m][n] = __builtin_amdgcn_mfma_f32_16x16x32_bf16(Bt[n][k], At[m][k], acc[ai][bj][m][n], 0, 0, 0); __builtin_amdgcn_s_setprio(0); } while (0)
; #define PG8_WAIT_V(n) asm volatile("s_waitcnt vmcnt(" #n ")" ::: "memory")
; #define PG8_WAIT_L(n) asm volatile("s_waitcnt lgkmcnt(" #n ")" ::: "memory")
; #define PG8_BAR __builtin_amdgcn_s_barrier()
; #define PG8_SCHED __builtin_amdgcn_sched_barrier(0)
; template <class Epi, class Sched, bool ALIGN_EPI = false, bool SP2 = false>
; __device__ __forceinline__ void gemm_phase(PG8_LAS unsigned char* lds, const Gemm g, const Sched& S, const Epi& E) {
;     ...
;             PG8_LDB(B0, 1, 0); PG8_LDB(B1, 1, 1); PG8_SCHED; PG8_LDA(At, 1, 0); PG8_STAGEA(PG8_SA(0, 1), a2 + hstep, voffA);
;             PG8_WAIT_V(8); PG8_WAIT_L(0); PG8_BAR; PG8_MMA(0, 0, At, B0); PG8_MMA(0, 1, At, B1); PG8_BAR; PG8_SCHED;
;             PG8_LDA(At, 1, 1); PG8_STAGEB(PG8_SB(1, 0), b3, voffB); PG8_STAGEB(PG8_SB(1, 1), b3 + hstep, voffB); PG8_STAGEA(PG8_SA(1, 0), a3, voffA);
;             PG8_WAIT_V(8); PG8_WAIT_L(0); PG8_BAR; PG8_MMA(1, 0, At, B0); PG8_MMA(1, 1, At, B1); PG8_BAR; PG8_SCHED;
;     ...
;         if (!has_next) break;
;         cur = nxt; cA = nA; cB = nB; ++ui;
	ds_read_b128 v[132:135], v130
	ds_read_b128 v[136:139], v130 offset:1024
	ds_read_b128 v[140:143], v130 offset:2048
	ds_read_b128 v[144:147], v130 offset:3072
	ds_read_b128 v[148:151], v131
	ds_read_b128 v[152:155], v131 offset:1024
	ds_read_b128 v[156:159], v131 offset:2048
	ds_read_b128 v[160:163], v131 offset:3072
	s_add_i32 s65, s63, 0x160000
	s_mov_b32 m0, s45
	ds_read_b128 v[164:167], v204 offset:32768
	ds_read_b128 v[168:171], v204 offset:33792
	ds_read_b128 v[172:175], v204 offset:34816
	ds_read_b128 v[176:179], v204 offset:35840
	ds_read_b128 v[180:183], v204 offset:36864
	ds_read_b128 v[184:187], v204 offset:37888
	ds_read_b128 v[188:191], v204 offset:38912
	ds_read_b128 v[208:211], v204 offset:39936
	buffer_load_dwordx4 v200, s[28:31], s65 offen lds
	s_mov_b32 m0, s47
	s_nop 0
	buffer_load_dwordx4 v201, s[28:31], s65 offen lds
	s_waitcnt vmcnt(8)
	s_waitcnt lgkmcnt(0)
	s_setprio 1
	s_barrier
	v_mfma_f32_16x16x32_bf16 v[126:129], v[132:135], v[164:167], v[126:129]
	v_mfma_f32_16x16x32_bf16 v[122:125], v[140:143], v[164:167], v[122:125]
	v_mfma_f32_16x16x32_bf16 v[114:117], v[132:135], v[172:175], v[114:117]
	v_mfma_f32_16x16x32_bf16 v[106:109], v[140:143], v[172:175], v[106:109]
	v_mfma_f32_16x16x32_bf16 v[98:101], v[132:135], v[180:183], v[98:101]
	v_mfma_f32_16x16x32_bf16 v[90:93], v[140:143], v[180:183], v[90:93]
	v_mfma_f32_16x16x32_bf16 v[82:85], v[132:135], v[188:191], v[82:85]
	v_mfma_f32_16x16x32_bf16 v[74:77], v[140:143], v[188:191], v[74:77]
	v_mfma_f32_16x16x32_bf16 v[126:129], v[136:139], v[168:171], v[126:129]
	v_mfma_f32_16x16x32_bf16 v[122:125], v[144:147], v[168:171], v[122:125]
	v_mfma_f32_16x16x32_bf16 v[114:117], v[136:139], v[176:179], v[114:117]
	v_mfma_f32_16x16x32_bf16 v[106:109], v[144:147], v[176:179], v[106:109]
	v_mfma_f32_16x16x32_bf16 v[98:101], v[136:139], v[184:187], v[98:101]
	v_mfma_f32_16x16x32_bf16 v[90:93], v[144:147], v[184:187], v[90:93]
	v_mfma_f32_16x16x32_bf16 v[82:85], v[136:139], v[208:211], v[82:85]
	v_mfma_f32_16x16x32_bf16 v[74:77], v[144:147], v[208:211], v[74:77]
	v_mfma_f32_16x16x32_bf16 v[118:121], v[148:151], v[164:167], v[118:121]
	v_mfma_f32_16x16x32_bf16 v[110:113], v[156:159], v[164:167], v[110:113]
	v_mfma_f32_16x16x32_bf16 v[102:105], v[148:151], v[172:175], v[102:105]
	v_mfma_f32_16x16x32_bf16 v[94:97], v[156:159], v[172:175], v[94:97]
	v_mfma_f32_16x16x32_bf16 v[86:89], v[148:151], v[180:183], v[86:89]
	v_mfma_f32_16x16x32_bf16 v[78:81], v[156:159], v[180:183], v[78:81]
	v_mfma_f32_16x16x32_bf16 v[70:73], v[148:151], v[188:191], v[70:73]
	v_mfma_f32_16x16x32_bf16 v[66:69], v[156:159], v[188:191], v[66:69]
	v_mfma_f32_16x16x32_bf16 v[118:121], v[152:155], v[168:171], v[118:121]
	v_mfma_f32_16x16x32_bf16 v[110:113], v[160:163], v[168:171], v[110:113]
	v_mfma_f32_16x16x32_bf16 v[102:105], v[152:155], v[176:179], v[102:105]
	v_mfma_f32_16x16x32_bf16 v[94:97], v[160:163], v[176:179], v[94:97]
	v_mfma_f32_16x16x32_bf16 v[86:89], v[152:155], v[184:187], v[86:89]
	v_mfma_f32_16x16x32_bf16 v[78:81], v[160:163], v[184:187], v[78:81]
	v_mfma_f32_16x16x32_bf16 v[70:73], v[152:155], v[208:211], v[70:73]
	v_mfma_f32_16x16x32_bf16 v[66:69], v[160:163], v[208:211], v[66:69]
	s_setprio 0
	s_barrier
	s_mov_b32 m0, s49
	s_add_i32 s65, s64, 0x80
	ds_read_b128 v[164:167], v204 offset:49152
	ds_read_b128 v[168:171], v204 offset:50176
	ds_read_b128 v[172:175], v204 offset:51200
	ds_read_b128 v[176:179], v204 offset:52224
	ds_read_b128 v[180:183], v204 offset:53248
	ds_read_b128 v[184:187], v204 offset:54272
	ds_read_b128 v[188:191], v204 offset:55296
	ds_read_b128 v[208:211], v204 offset:56320
	buffer_load_dwordx4 v200, s[12:15], s65 offen lds
	s_mov_b32 m0, s50
	s_add_i32 s64, s64, 0x160080
	buffer_load_dwordx4 v201, s[12:15], s65 offen lds
	s_mov_b32 m0, s57
	s_addk_i32 s63, 0x80
	buffer_load_dwordx4 v200, s[12:15], s64 offen lds
	s_mov_b32 m0, s58
	s_nop 0
	buffer_load_dwordx4 v201, s[12:15], s64 offen lds
	s_mov_b32 m0, s51
	s_nop 0
	buffer_load_dwordx4 v200, s[28:31], s63 offen lds
	s_mov_b32 m0, s56
	s_nop 0
	buffer_load_dwordx4 v201, s[28:31], s63 offen lds
	s_waitcnt vmcnt(8)
	s_waitcnt lgkmcnt(0)
	s_setprio 1
	s_barrier
	v_mfma_f32_16x16x32_bf16 v[62:65], v[132:135], v[164:167], v[62:65]
	v_mfma_f32_16x16x32_bf16 v[58:61], v[140:143], v[164:167], v[58:61]
	v_mfma_f32_16x16x32_bf16 v[50:53], v[132:135], v[172:175], v[50:53]
	v_mfma_f32_16x16x32_bf16 v[42:45], v[140:143], v[172:175], v[42:45]
	v_mfma_f32_16x16x32_bf16 v[34:37], v[132:135], v[180:183], v[34:37]
	v_mfma_f32_16x16x32_bf16 v[26:29], v[140:143], v[180:183], v[26:29]
	v_mfma_f32_16x16x32_bf16 v[18:21], v[132:135], v[188:191], v[18:21]
	v_mfma_f32_16x16x32_bf16 v[10:13], v[140:143], v[188:191], v[10:13]
	v_mfma_f32_16x16x32_bf16 v[62:65], v[136:139], v[168:171], v[62:65]
	v_mfma_f32_16x16x32_bf16 v[58:61], v[144:147], v[168:171], v[58:61]
	v_mfma_f32_16x16x32_bf16 v[50:53], v[136:139], v[176:179], v[50:53]
	v_mfma_f32_16x16x32_bf16 v[42:45], v[144:147], v[176:179], v[42:45]
	v_mfma_f32_16x16x32_bf16 v[34:37], v[136:139], v[184:187], v[34:37]
	v_mfma_f32_16x16x32_bf16 v[26:29], v[144:147], v[184:187], v[26:29]
	v_mfma_f32_16x16x32_bf16 v[18:21], v[136:139], v[208:211], v[18:21]
	v_mfma_f32_16x16x32_bf16 v[10:13], v[144:147], v[208:211], v[10:13]
	v_mfma_f32_16x16x32_bf16 v[54:57], v[148:151], v[164:167], v[54:57]
	v_mfma_f32_16x16x32_bf16 v[46:49], v[156:159], v[164:167], v[46:49]
	v_mfma_f32_16x16x32_bf16 v[38:41], v[148:151], v[172:175], v[38:41]
	v_mfma_f32_16x16x32_bf16 v[30:33], v[156:159], v[172:175], v[30:33]
	v_mfma_f32_16x16x32_bf16 v[22:25], v[148:151], v[180:183], v[22:25]
	v_mfma_f32_16x16x32_bf16 v[14:17], v[156:159], v[180:183], v[14:17]
	v_mfma_f32_16x16x32_bf16 v[6:9], v[148:151], v[188:191], v[6:9]
	v_mfma_f32_16x16x32_bf16 v[2:5], v[156:159], v[188:191], v[2:5]
	v_mfma_f32_16x16x32_bf16 v[54:57], v[152:155], v[168:171], v[54:57]
	v_mfma_f32_16x16x32_bf16 v[46:49], v[160:163], v[168:171], v[46:49]
	v_mfma_f32_16x16x32_bf16 v[38:41], v[152:155], v[176:179], v[38:41]
	v_mfma_f32_16x16x32_bf16 v[30:33], v[160:163], v[176:179], v[30:33]
	v_mfma_f32_16x16x32_bf16 v[22:25], v[152:155], v[184:187], v[22:25]
	v_mfma_f32_16x16x32_bf16 v[14:17], v[160:163], v[184:187], v[14:17]
	v_mfma_f32_16x16x32_bf16 v[6:9], v[152:155], v[208:211], v[6:9]
	v_mfma_f32_16x16x32_bf16 v[2:5], v[160:163], v[208:211], v[2:5]
	s_setprio 0
	s_barrier
	s_add_i32 s23, s23, 2
	s_add_u32 s34, s34, 0x100
	s_addc_u32 s35, s35, 0
	s_cmpk_gt_u32 s23, 0x55
	s_cbranch_scc0 .LBB0_941
	s_and_b64 vcc, exec, s[2:3]
	s_cbranch_vccz .LBB0_927
	s_mov_b32 s16, s61
	s_mov_b32 s37, s62
	s_mov_b64 s[18:19], s[4:5]
	s_mov_b64 s[20:21], s[24:25]
	s_mov_b32 s48, s22
	s_branch .LBB0_927
